# attention loop edges: end-of-iteration branch ladder reduced to one scalar test with a barrier copy on each side; post-barrier PV MFMA issued after the next four K reads
# baseline (speedup 1.0000x reference)
; __device__ __forceinline__ void finishSM(f32x16& p0, f32x16& p1, float alpha, float& l_reg, bf16x8& pa0, bf16x8& pa1, bf16x8& pa2, bf16x8& pa3) {
;   for (int r = 0; r < 16; ++r) p1[r] = __builtin_amdgcn_exp2f(p1[r]);
;   float ps = 0; for (int r = 0; r < 16; ++r) ps += p0[r]; for (int r = 0; r < 16; ++r) ps += p1[r];
;   asm volatile("" : "+v"(ps));
;   l_reg = l_reg * alpha + ps;
;     ...
;   PK4(p0, 0, pa0); PK4(p0, 8, pa1); PK4(p1, 0, pa2); PK4(p1, 8, pa3);
;     ...
; }
; __device__ __forceinline__ void qkt(f32x16& p0, f32x16& p1, const bf16* Ks, const bf16x8* qr, int r32, int hi) {
;   p0 = f32x16{}; p1 = f32x16{};
;   for (int d0 = 0; d0 < 8; ++d0) { int cb = (d0 * 16 + hi * 8) * 2;
;     bf16x8 b0 = *reinterpret_cast<const bf16x8*>((const char*)Ks + KSWZ(r32, cb));
;     bf16x8 b1 = *reinterpret_cast<const bf16x8*>((const char*)Ks + KSWZ(32 + r32, cb));
;     p0 = __builtin_amdgcn_mfma_f32_32x32x16_bf16(b0, qr[d0], p0, 0, 0, 0);
;     p1 = __builtin_amdgcn_mfma_f32_32x32x16_bf16(b1, qr[d0], p1, 0, 0, 0); }
; }
; __device__ __forceinline__ int v_st(int k, int c) { const int kk = k;
;   return ((kk >> 3) * 4 + (c >> 5)) * 512 + ((kk & 7) * 32 + (c & 31)) * 2; }
; __device__ __forceinline__ int v_rd_base(int lane) { return ((lane & 3) << 3) | (((lane >> 2) & 3) << 6) | (((lane >> 4) & 1) << 5) | (((lane >> 5) & 1) << 8); }
; template <int OFF> __device__ __forceinline__ s16x4 tr_read(int vb) {
;   s16x4 r; asm volatile("ds_read_b64_tr_b16 %0, %1 offset:%2" : "=&v"(r) : "v"(vb), "i"(OFF) : "memory"); return r;
; }
; template <int D0> __device__ __forceinline__ void pv_one(f32x16& od, int vb, bf16x8 pa0, bf16x8 pa1, bf16x8 pa2, bf16x8 pa3) {
;   const s16x4 l0 = tr_read<v_rd_off(D0, 0, 0)>(vb), h0 = tr_read<v_rd_off(D0, 0, 1)>(vb), l1 = tr_read<v_rd_off(D0, 1, 0)>(vb), h1 = tr_read<v_rd_off(D0, 1, 1)>(vb);
;   const s16x4 l2 = tr_read<v_rd_off(D0, 2, 0)>(vb), h2 = tr_read<v_rd_off(D0, 2, 1)>(vb), l3 = tr_read<v_rd_off(D0, 3, 0)>(vb), h3 = tr_read<v_rd_off(D0, 3, 1)>(vb);
;   asm volatile("s_waitcnt lgkmcnt(0)" ::: "memory"); SBAR();
;     ...
;   od = __builtin_amdgcn_mfma_f32_32x32x16_bf16(pa0, PK(l0, h0), od, 0, 0, 0);
;   od = __builtin_amdgcn_mfma_f32_32x32x16_bf16(pa1, PK(l1, h1), od, 0, 0, 0);
;   od = __builtin_amdgcn_mfma_f32_32x32x16_bf16(pa2, PK(l2, h2), od, 0, 0, 0);
;   od = __builtin_amdgcn_mfma_f32_32x32x16_bf16(pa3, PK(l3, h3), od, 0, 0, 0);
;     ...
; }
.Lat461_a_go:
	s_waitcnt lgkmcnt(3)
	v_mfma_f32_32x32x16_bf16 v[96:111], v[80:83], v[136:139], 0
	v_exp_f32_e32 v238, v64
	v_add_f32_e32 v64, v197, v196
	v_add_f32_e32 v64, v193, v64
	v_add_f32_e32 v64, v195, v64
	s_waitcnt lgkmcnt(2)
	v_mfma_f32_32x32x16_bf16 v[80:95], v[84:87], v[136:139], 0
	v_add_f32_e32 v64, v191, v64
	v_add_f32_e32 v64, v194, v64
	v_add_f32_e32 v64, v190, v64
	v_add_f32_e32 v64, v192, v64
	v_add_f32_e32 v64, v169, v64
	v_add_f32_e32 v64, v171, v64
	s_waitcnt lgkmcnt(1)
	v_mfma_f32_32x32x16_bf16 v[96:111], v[198:201], v[140:143], v[96:111]
	v_add_f32_e32 v64, v167, v64
	v_add_f32_e32 v64, v170, v64
	v_add_f32_e32 v64, v165, v64
	v_add_f32_e32 v64, v168, v64
	v_add_f32_e32 v64, v164, v64
	v_add_f32_e32 v64, v166, v64
	v_exp_f32_e32 v239, v68
	s_waitcnt lgkmcnt(0)
	v_mfma_f32_32x32x16_bf16 v[80:95], v[202:205], v[140:143], v[80:95]
	ds_read_b128 v[198:201], v180 offset:16384
	ds_read_b128 v[202:205], v180 offset:24576
	v_add_f32_e32 v64, v238, v64
	v_exp_f32_e32 v240, v69
	v_exp_f32_e32 v241, v70
	v_exp_f32_e32 v242, v71
	s_waitcnt lgkmcnt(1)
	v_mfma_f32_32x32x16_bf16 v[96:111], v[198:201], v[132:135], v[96:111]
	ds_read_b128 v[198:201], v181 offset:16384
	ds_read_b128 v[206:209], v181 offset:24576
	ds_read_b128 v[210:213], v182 offset:16384
	ds_read_b128 v[214:217], v182 offset:24576
	ds_read_b128 v[218:221], v183 offset:16384
	ds_read_b128 v[222:225], v183 offset:24576
	v_exp_f32_e32 v243, v76
	v_exp_f32_e32 v244, v77
	v_exp_f32_e32 v245, v78
	v_exp_f32_e32 v79, v79
	s_waitcnt lgkmcnt(6)
	v_mfma_f32_32x32x16_bf16 v[80:95], v[202:205], v[132:135], v[80:95]
	ds_read_b128 v[202:205], v184 offset:16384
	ds_read_b128 v[226:229], v184 offset:24576
	ds_read_b128 v[230:233], v185 offset:16384
	ds_read_b128 v[234:237], v185 offset:24576
	s_waitcnt lgkmcnt(9)
	v_mfma_f32_32x32x16_bf16 v[96:111], v[198:201], v[128:131], v[96:111]
	v_exp_f32_e32 v199, v65
	v_exp_f32_e32 v200, v66
	v_exp_f32_e32 v201, v67
	v_add_f32_e32 v64, v199, v64
	v_add_f32_e32 v64, v200, v64
	v_add_f32_e32 v64, v201, v64
	s_waitcnt lgkmcnt(8)
	v_mfma_f32_32x32x16_bf16 v[80:95], v[206:209], v[128:131], v[80:95]
	v_exp_f32_e32 v206, v72
	v_add_f32_e32 v64, v239, v64
	v_exp_f32_e32 v207, v73
	v_add_f32_e32 v64, v240, v64
	v_exp_f32_e32 v208, v74
	v_add_f32_e32 v64, v241, v64
	v_exp_f32_e32 v209, v75
	s_waitcnt lgkmcnt(7)
	v_mfma_f32_32x32x16_bf16 v[96:111], v[210:213], v[124:127], v[96:111]
	v_add_f32_e32 v64, v242, v64
	v_add_f32_e32 v64, v206, v64
	v_add_f32_e32 v64, v207, v64
	v_add_f32_e32 v64, v208, v64
	v_add_f32_e32 v64, v209, v64
	v_add_f32_e32 v64, v243, v64
	v_add_f32_e32 v64, v244, v64
	s_waitcnt lgkmcnt(6)
	v_mfma_f32_32x32x16_bf16 v[80:95], v[214:217], v[124:127], v[80:95]
	v_add_f32_e32 v64, v245, v64
	v_add_f32_e32 v198, v79, v64
	v_cvt_pk_bf16_f32 v64, v196, v197
	v_cvt_pk_bf16_f32 v65, v193, v195
	v_cvt_pk_bf16_f32 v66, v191, v194
	v_cvt_pk_bf16_f32 v67, v190, v192
	s_waitcnt lgkmcnt(5)
	v_mfma_f32_32x32x16_bf16 v[96:111], v[218:221], v[120:123], v[96:111]
	v_cvt_pk_bf16_f32 v68, v169, v171
	v_cvt_pk_bf16_f32 v69, v167, v170
	v_cvt_pk_bf16_f32 v70, v165, v168
	v_cvt_pk_bf16_f32 v71, v164, v166
	v_cvt_pk_bf16_f32 v72, v238, v199
	v_cvt_pk_bf16_f32 v73, v200, v201
	v_cvt_pk_bf16_f32 v74, v239, v240
	s_waitcnt lgkmcnt(4)
	v_mfma_f32_32x32x16_bf16 v[80:95], v[222:225], v[120:123], v[80:95]
	v_cvt_pk_bf16_f32 v75, v241, v242
	v_cvt_pk_bf16_f32 v76, v206, v207
	v_cvt_pk_bf16_f32 v77, v208, v209
	v_cvt_pk_bf16_f32 v78, v243, v244
	v_cvt_pk_bf16_f32 v79, v245, v79
	s_waitcnt lgkmcnt(3)
	v_mfma_f32_32x32x16_bf16 v[96:111], v[202:205], v[116:119], v[96:111]
	s_add_i32 s33, s40, 0x8000
	s_and_b32 s43, s33, 0xc000
	ds_read_b64_tr_b16 v[190:191], v176
	ds_read_b64_tr_b16 v[192:193], v176 offset:2048
	ds_read_b64_tr_b16 v[194:195], v176 offset:4096
	ds_read_b64_tr_b16 v[196:197], v176 offset:6144
	s_waitcnt lgkmcnt(6)
	v_mfma_f32_32x32x16_bf16 v[80:95], v[226:229], v[116:119], v[80:95]
	ds_read_b64_tr_b16 v[200:201], v176 offset:8192
	ds_read_b64_tr_b16 v[202:203], v176 offset:10240
	ds_read_b64_tr_b16 v[204:205], v176 offset:12288
	ds_read_b64_tr_b16 v[206:207], v176 offset:14336
	s_add_i32 s74, s40, 0x4000
	s_and_b32 s74, s74, 0xc000
	s_add_u32 s98, s38, s22
	s_addc_u32 s99, s39, s23
	s_add_i32 s41, s67, s74
	s_add_u32 s100, s38, s24
	s_addc_u32 s101, s39, s25
	s_mov_b32 m0, s41
	s_add_i32 s74, s72, s74
	global_load_lds_dwordx4 v156, s[98:99]
	s_waitcnt lgkmcnt(9)
	v_mfma_f32_32x32x16_bf16 v[96:111], v[230:233], v[112:115], v[96:111]
	s_add_i32 m0, s41, 0x2000
	s_nop 0
	global_load_lds_dwordx4 v158, s[98:99]
	s_mov_b32 m0, s74
	s_nop 0
	global_load_lds_dwordx4 v162, s[100:101]
	s_waitcnt lgkmcnt(8)
	v_mfma_f32_32x32x16_bf16 v[80:95], v[234:237], v[112:115], v[80:95]
	s_add_i32 m0, s74, 0x2000
	s_nop 0
	global_load_lds_dwordx4 v160, s[100:101]
	s_nop 0
	s_waitcnt lgkmcnt(6)
	v_mfma_f32_32x32x16_bf16 v[48:63], v[64:67], v[190:193], v[48:63]
	v_exp_f32_e32 v232, v96
	ds_read_b64_tr_b16 v[190:191], v176 offset:512
	ds_read_b64_tr_b16 v[192:193], v176 offset:2560
	s_waitcnt lgkmcnt(6)
	v_mfma_f32_32x32x16_bf16 v[48:63], v[68:71], v[194:197], v[48:63]
	v_exp_f32_e32 v233, v97
	ds_read_b64_tr_b16 v[194:195], v176 offset:4608
	ds_read_b64_tr_b16 v[196:197], v176 offset:6656
	s_waitcnt lgkmcnt(6)
	v_mfma_f32_32x32x16_bf16 v[48:63], v[72:75], v[200:203], v[48:63]
	v_exp_f32_e32 v234, v98
	ds_read_b64_tr_b16 v[200:201], v176 offset:8704
	ds_read_b64_tr_b16 v[202:203], v176 offset:10752
	ds_read_b64_tr_b16 v[208:209], v176 offset:12800
	ds_read_b64_tr_b16 v[210:211], v176 offset:14848
	s_waitcnt lgkmcnt(8)
; #define SBAR() __builtin_amdgcn_sched_barrier(0)
; #define PUBLISH(n) do { asm volatile("s_waitcnt vmcnt(" #n ")" ::: "memory"); asm volatile("s_waitcnt lgkmcnt(0)" ::: "memory"); __builtin_amdgcn_s_barrier(); SBAR(); } while (0)
; template <int D0> __device__ __forceinline__ void pv_one(f32x16& od, int vb, bf16x8 pa0, bf16x8 pa1, bf16x8 pa2, bf16x8 pa3) {
;   const s16x4 l0 = tr_read<v_rd_off(D0, 0, 0)>(vb), h0 = tr_read<v_rd_off(D0, 0, 1)>(vb), l1 = tr_read<v_rd_off(D0, 1, 0)>(vb), h1 = tr_read<v_rd_off(D0, 1, 1)>(vb);
;   const s16x4 l2 = tr_read<v_rd_off(D0, 2, 0)>(vb), h2 = tr_read<v_rd_off(D0, 2, 1)>(vb), l3 = tr_read<v_rd_off(D0, 3, 0)>(vb), h3 = tr_read<v_rd_off(D0, 3, 1)>(vb);
;   asm volatile("s_waitcnt lgkmcnt(0)" ::: "memory"); SBAR();
;     ...
;   od = __builtin_amdgcn_mfma_f32_32x32x16_bf16(pa0, PK(l0, h0), od, 0, 0, 0);
;   od = __builtin_amdgcn_mfma_f32_32x32x16_bf16(pa1, PK(l1, h1), od, 0, 0, 0);
;   od = __builtin_amdgcn_mfma_f32_32x32x16_bf16(pa2, PK(l2, h2), od, 0, 0, 0);
;   od = __builtin_amdgcn_mfma_f32_32x32x16_bf16(pa3, PK(l3, h3), od, 0, 0, 0);
;     ...
; }
; __device__ __forceinline__ void pv_d0(f32x16* o, int vb, bf16x8 pa0, bf16x8 pa1, bf16x8 pa2, bf16x8 pa3) {
;   pv_one<0>(o[0], vb, pa0, pa1, pa2, pa3); pv_one<1>(o[1], vb, pa0, pa1, pa2, pa3); pv_one<2>(o[2], vb, pa0, pa1, pa2, pa3); pv_one<3>(o[3], vb, pa0, pa1, pa2, pa3);
; }
; template <typename TQ> ...
;     ...
;   for (int j = 1; j + 1 < NT; j += 2) {
;     SBAR(); qkt(pB0, pB1, (const bf16*)(K_lds + (j & 3) * (int)SHM_K), qr, r32, hi);
;     finishSM(pA0, pA1, alA, l_reg, pa0, pa1, pa2, pa3); SBAR();
;     DMA_TILE(j + 2, (j + 2) & 3); SBAR();
;     pv_d0(o, vb0 + ((j - 1) & 3) * (int)SHM_V, pa0, pa1, pa2, pa3); partialSM<true>(pB0, pB1, m_reg, mnB, alB);
;     PUBLISH(4);
;     SBAR(); qkt(pA0, pA1, (const bf16*)(K_lds + ((j + 1) & 3) * (int)SHM_K), qr, r32, hi);
;     finishSM(pB0, pB1, alB, l_reg, pa0, pa1, pa2, pa3); SBAR();
;     if (j + 3 < NT) { DMA_TILE(j + 3, (j + 3) & 3); } SBAR();
;     pv_d0(o, vb0 + (j & 3) * (int)SHM_V, pa0, pa1, pa2, pa3); partialSM<true>(pA0, pA1, m_reg, mnA, alA);
;     if (j + 3 < NT) { PUBLISH(4); } else { PUBLISH(0); }
	v_mfma_f32_32x32x16_bf16 v[48:63], v[76:79], v[204:207], v[48:63]
	v_exp_f32_e32 v235, v99
	s_waitcnt lgkmcnt(6)
	v_mfma_f32_32x32x16_bf16 v[32:47], v[64:67], v[190:193], v[32:47]
	v_exp_f32_e32 v236, v100
	ds_read_b64_tr_b16 v[190:191], v176 offset:1024
	ds_read_b64_tr_b16 v[192:193], v176 offset:3072
	s_waitcnt lgkmcnt(6)
	v_mfma_f32_32x32x16_bf16 v[32:47], v[68:71], v[194:197], v[32:47]
	v_exp_f32_e32 v237, v101
	ds_read_b64_tr_b16 v[194:195], v176 offset:5120
	ds_read_b64_tr_b16 v[196:197], v176 offset:7168
	s_waitcnt lgkmcnt(6)
	v_mfma_f32_32x32x16_bf16 v[32:47], v[72:75], v[200:203], v[32:47]
	v_exp_f32_e32 v238, v102
	ds_read_b64_tr_b16 v[200:201], v176 offset:9216
	ds_read_b64_tr_b16 v[202:203], v176 offset:11264
	ds_read_b64_tr_b16 v[204:205], v176 offset:13312
	ds_read_b64_tr_b16 v[206:207], v176 offset:15360
	s_waitcnt lgkmcnt(8)
	v_mfma_f32_32x32x16_bf16 v[32:47], v[76:79], v[208:211], v[32:47]
	v_exp_f32_e32 v239, v103
	v_exp_f32_e32 v240, v104
	s_waitcnt lgkmcnt(6)
	v_mfma_f32_32x32x16_bf16 v[16:31], v[64:67], v[190:193], v[16:31]
	v_exp_f32_e32 v241, v105
	ds_read_b64_tr_b16 v[190:191], v176 offset:1536
	ds_read_b64_tr_b16 v[192:193], v176 offset:3584
	s_waitcnt lgkmcnt(6)
	v_mfma_f32_32x32x16_bf16 v[16:31], v[68:71], v[194:197], v[16:31]
	v_exp_f32_e32 v242, v106
	ds_read_b64_tr_b16 v[194:195], v176 offset:5632
	ds_read_b64_tr_b16 v[196:197], v176 offset:7680
	s_waitcnt lgkmcnt(6)
	v_mfma_f32_32x32x16_bf16 v[16:31], v[72:75], v[200:203], v[16:31]
	v_exp_f32_e32 v243, v107
	ds_read_b64_tr_b16 v[200:201], v176 offset:9728
	ds_read_b64_tr_b16 v[202:203], v176 offset:11776
	ds_read_b64_tr_b16 v[208:209], v176 offset:13824
	ds_read_b64_tr_b16 v[210:211], v176 offset:15872
	s_waitcnt lgkmcnt(8)
	v_mfma_f32_32x32x16_bf16 v[16:31], v[76:79], v[204:207], v[16:31]
	v_exp_f32_e32 v244, v108
	s_waitcnt lgkmcnt(6)
	v_mfma_f32_32x32x16_bf16 v[0:15], v[64:67], v[190:193], v[0:15]
	v_exp_f32_e32 v245, v109
	s_waitcnt lgkmcnt(4)
	v_mfma_f32_32x32x16_bf16 v[0:15], v[68:71], v[194:197], v[0:15]
	v_exp_f32_e32 v246, v110
	s_waitcnt lgkmcnt(2)
	v_mfma_f32_32x32x16_bf16 v[0:15], v[72:75], v[200:203], v[0:15]
	v_exp_f32_e32 v247, v111
	s_waitcnt vmcnt(4)
	s_waitcnt lgkmcnt(0)
	s_barrier
	s_and_b32 s40, s40, 0xc000
	s_add_i32 s40, s57, s40
	ds_read_b128 v[64:67], v178 offset:32768
	ds_read_b128 v[68:71], v178 offset:40960
	ds_read_b128 v[190:193], v179 offset:32768
	ds_read_b128 v[194:197], v179 offset:40960
	v_mfma_f32_32x32x16_bf16 v[0:15], v[76:79], v[208:211], v[0:15]
	s_waitcnt lgkmcnt(3)
	v_mfma_f32_32x32x16_bf16 v[96:111], v[64:67], v[136:139], 0
	v_exp_f32_e32 v80, v80
	v_exp_f32_e32 v81, v81
	v_exp_f32_e32 v82, v82
	v_exp_f32_e32 v83, v83
	v_exp_f32_e32 v87, v87
	v_exp_f32_e32 v248, v93
	v_exp_f32_e32 v249, v94
	s_waitcnt lgkmcnt(2)
	v_mfma_f32_32x32x16_bf16 v[64:79], v[68:71], v[136:139], 0
	s_waitcnt lgkmcnt(1)
	v_mfma_f32_32x32x16_bf16 v[96:111], v[190:193], v[140:143], v[96:111]
	s_waitcnt lgkmcnt(0)
	v_mfma_f32_32x32x16_bf16 v[64:79], v[194:197], v[140:143], v[64:79]
	ds_read_b128 v[190:193], v180 offset:32768
	ds_read_b128 v[194:197], v180 offset:40960
	s_waitcnt lgkmcnt(1)
	v_mfma_f32_32x32x16_bf16 v[96:111], v[190:193], v[132:135], v[96:111]
	ds_read_b128 v[190:193], v181 offset:32768
	ds_read_b128 v[200:203], v181 offset:40960
	ds_read_b128 v[204:207], v182 offset:32768
	ds_read_b128 v[208:211], v182 offset:40960
	ds_read_b128 v[212:215], v183 offset:32768
	ds_read_b128 v[216:219], v183 offset:40960
	s_waitcnt lgkmcnt(6)
	v_mfma_f32_32x32x16_bf16 v[64:79], v[194:197], v[132:135], v[64:79]
	ds_read_b128 v[194:197], v184 offset:32768
	ds_read_b128 v[220:223], v184 offset:40960
	ds_read_b128 v[224:227], v185 offset:32768
	ds_read_b128 v[228:231], v185 offset:40960
	s_waitcnt lgkmcnt(9)
	v_mfma_f32_32x32x16_bf16 v[96:111], v[190:193], v[128:131], v[96:111]
	s_cmp_ge_u32 s73, s37
	s_cselect_b64 s[40:41], -1, 0
	s_and_b64 vcc, exec, s[40:41]
	s_cbranch_vccnz .LBB0_463
	s_add_i32 s74, s67, s43
	s_add_u32 s98, s38, s26
	s_addc_u32 s99, s39, s27
	s_mov_b32 m0, s74
	s_add_i32 s43, s72, s43
	global_load_lds_dwordx4 v156, s[98:99]
	s_add_u32 s100, s38, s28
	s_addc_u32 s101, s39, s29
	s_add_i32 m0, s74, 0x2000
	s_nop 0
	global_load_lds_dwordx4 v158, s[98:99]
	s_mov_b32 m0, s43
	s_nop 0
	global_load_lds_dwordx4 v162, s[100:101]
	s_add_i32 m0, s43, 0x2000
	s_nop 0
	global_load_lds_dwordx4 v160, s[100:101]
; __device__ __forceinline__ void finishSM(f32x16& p0, f32x16& p1, float alpha, float& l_reg, bf16x8& pa0, bf16x8& pa1, bf16x8& pa2, bf16x8& pa3) {
;   for (int r = 0; r < 16; ++r) p1[r] = __builtin_amdgcn_exp2f(p1[r]);
;   float ps = 0; for (int r = 0; r < 16; ++r) ps += p0[r]; for (int r = 0; r < 16; ++r) ps += p1[r];
;   asm volatile("" : "+v"(ps));
;   l_reg = l_reg * alpha + ps;
;     ...
;   PK4(p0, 0, pa0); PK4(p0, 8, pa1); PK4(p1, 0, pa2); PK4(p1, 8, pa3);
;     ...
; }
; __device__ __forceinline__ void qkt(f32x16& p0, f32x16& p1, const bf16* Ks, const bf16x8* qr, int r32, int hi) {
;   p0 = f32x16{}; p1 = f32x16{};
;   for (int d0 = 0; d0 < 8; ++d0) { int cb = (d0 * 16 + hi * 8) * 2;
;     bf16x8 b0 = *reinterpret_cast<const bf16x8*>((const char*)Ks + KSWZ(r32, cb));
;     bf16x8 b1 = *reinterpret_cast<const bf16x8*>((const char*)Ks + KSWZ(32 + r32, cb));
;     p0 = __builtin_amdgcn_mfma_f32_32x32x16_bf16(b0, qr[d0], p0, 0, 0, 0);
;     p1 = __builtin_amdgcn_mfma_f32_32x32x16_bf16(b1, qr[d0], p1, 0, 0, 0); }
; }
; __device__ __forceinline__ int v_st(int k, int c) { const int kk = k;
;   return ((kk >> 3) * 4 + (c >> 5)) * 512 + ((kk & 7) * 32 + (c & 31)) * 2; }
; __device__ __forceinline__ int v_rd_base(int lane) { return ((lane & 3) << 3) | (((lane >> 2) & 3) << 6) | (((lane >> 4) & 1) << 5) | (((lane >> 5) & 1) << 8); }
; template <int OFF> __device__ __forceinline__ s16x4 tr_read(int vb) {
;   s16x4 r; asm volatile("ds_read_b64_tr_b16 %0, %1 offset:%2" : "=&v"(r) : "v"(vb), "i"(OFF) : "memory"); return r;
; }
; template <int D0> __device__ __forceinline__ void pv_one(f32x16& od, int vb, bf16x8 pa0, bf16x8 pa1, bf16x8 pa2, bf16x8 pa3) {
;   const s16x4 l0 = tr_read<v_rd_off(D0, 0, 0)>(vb), h0 = tr_read<v_rd_off(D0, 0, 1)>(vb), l1 = tr_read<v_rd_off(D0, 1, 0)>(vb), h1 = tr_read<v_rd_off(D0, 1, 1)>(vb);
;   const s16x4 l2 = tr_read<v_rd_off(D0, 2, 0)>(vb), h2 = tr_read<v_rd_off(D0, 2, 1)>(vb), l3 = tr_read<v_rd_off(D0, 3, 0)>(vb), h3 = tr_read<v_rd_off(D0, 3, 1)>(vb);
;   asm volatile("s_waitcnt lgkmcnt(0)" ::: "memory"); SBAR();
;     ...
;   od = __builtin_amdgcn_mfma_f32_32x32x16_bf16(pa0, PK(l0, h0), od, 0, 0, 0);
;   od = __builtin_amdgcn_mfma_f32_32x32x16_bf16(pa1, PK(l1, h1), od, 0, 0, 0);
;   od = __builtin_amdgcn_mfma_f32_32x32x16_bf16(pa2, PK(l2, h2), od, 0, 0, 0);
;   od = __builtin_amdgcn_mfma_f32_32x32x16_bf16(pa3, PK(l3, h3), od, 0, 0, 0);
;     ...
; }
.LBB0_463:
	v_exp_f32_e32 v190, v84
	v_add_f32_e32 v84, v233, v232
	v_add_f32_e32 v84, v234, v84
	v_add_f32_e32 v84, v235, v84
	v_add_f32_e32 v84, v236, v84
	v_add_f32_e32 v84, v237, v84
	s_waitcnt lgkmcnt(8)
	v_mfma_f32_32x32x16_bf16 v[64:79], v[200:203], v[128:131], v[64:79]
	v_add_f32_e32 v84, v238, v84
	v_add_f32_e32 v84, v239, v84
	v_add_f32_e32 v84, v240, v84
	v_add_f32_e32 v84, v241, v84
	v_add_f32_e32 v84, v242, v84
	v_add_f32_e32 v84, v243, v84
	v_add_f32_e32 v84, v244, v84
	s_waitcnt lgkmcnt(7)
	v_mfma_f32_32x32x16_bf16 v[96:111], v[204:207], v[124:127], v[96:111]
	v_add_f32_e32 v84, v245, v84
	v_add_f32_e32 v84, v246, v84
	v_add_f32_e32 v84, v247, v84
	v_add_f32_e32 v84, v80, v84
	v_exp_f32_e32 v191, v85
	v_add_f32_e32 v84, v81, v84
	v_exp_f32_e32 v192, v86
	s_waitcnt lgkmcnt(6)
	v_mfma_f32_32x32x16_bf16 v[64:79], v[208:211], v[124:127], v[64:79]
	v_add_f32_e32 v84, v82, v84
	v_add_f32_e32 v84, v83, v84
	v_exp_f32_e32 v193, v88
	v_add_f32_e32 v84, v190, v84
	v_exp_f32_e32 v200, v89
	v_add_f32_e32 v84, v191, v84
	v_exp_f32_e32 v201, v90
	s_waitcnt lgkmcnt(5)
	v_mfma_f32_32x32x16_bf16 v[96:111], v[212:215], v[120:123], v[96:111]
	v_add_f32_e32 v84, v192, v84
	v_exp_f32_e32 v202, v91
	v_add_f32_e32 v84, v87, v84
	v_exp_f32_e32 v203, v92
	v_add_f32_e32 v84, v193, v84
	v_add_f32_e32 v84, v200, v84
	v_add_f32_e32 v84, v201, v84
	s_waitcnt lgkmcnt(4)
	v_mfma_f32_32x32x16_bf16 v[64:79], v[216:219], v[120:123], v[64:79]
	v_exp_f32_e32 v204, v95
	v_add_f32_e32 v84, v202, v84
	v_add_f32_e32 v84, v203, v84
	v_add_f32_e32 v84, v248, v84
	v_add_f32_e32 v84, v249, v84
	v_add_f32_e32 v199, v204, v84
	s_waitcnt lgkmcnt(3)
	v_mfma_f32_32x32x16_bf16 v[96:111], v[194:197], v[116:119], v[96:111]
	v_cvt_pk_bf16_f32 v92, v232, v233
	v_cvt_pk_bf16_f32 v93, v234, v235
	v_cvt_pk_bf16_f32 v94, v236, v237
	v_cvt_pk_bf16_f32 v95, v238, v239
	v_cvt_pk_bf16_f32 v88, v240, v241
	v_cvt_pk_bf16_f32 v89, v242, v243
	v_cvt_pk_bf16_f32 v90, v244, v245
	s_waitcnt lgkmcnt(2)
	v_mfma_f32_32x32x16_bf16 v[64:79], v[220:223], v[116:119], v[64:79]
	v_cvt_pk_bf16_f32 v91, v246, v247
	v_cvt_pk_bf16_f32 v84, v80, v81
	v_cvt_pk_bf16_f32 v85, v82, v83
	v_cvt_pk_bf16_f32 v86, v190, v191
	v_cvt_pk_bf16_f32 v87, v192, v87
	v_cvt_pk_bf16_f32 v80, v193, v200
	v_cvt_pk_bf16_f32 v81, v201, v202
	ds_read_b64_tr_b16 v[164:165], v176 offset:16384
	ds_read_b64_tr_b16 v[166:167], v176 offset:18432
	ds_read_b64_tr_b16 v[168:169], v176 offset:20480
	ds_read_b64_tr_b16 v[170:171], v176 offset:22528
	s_waitcnt lgkmcnt(5)
	v_mfma_f32_32x32x16_bf16 v[96:111], v[224:227], v[112:115], v[96:111]
	v_cvt_pk_bf16_f32 v82, v203, v248
	v_cvt_pk_bf16_f32 v83, v249, v204
	ds_read_b64_tr_b16 v[190:191], v176 offset:24576
	ds_read_b64_tr_b16 v[192:193], v176 offset:26624
	ds_read_b64_tr_b16 v[194:195], v176 offset:28672
	ds_read_b64_tr_b16 v[196:197], v176 offset:30720
	s_waitcnt lgkmcnt(8)
	v_mfma_f32_32x32x16_bf16 v[64:79], v[228:231], v[112:115], v[64:79]
	s_nop 0
	s_waitcnt lgkmcnt(6)
	v_mfma_f32_32x32x16_bf16 v[48:63], v[92:95], v[164:167], v[48:63]
	ds_read_b64_tr_b16 v[164:165], v176 offset:16896
	ds_read_b64_tr_b16 v[166:167], v176 offset:18944
	s_waitcnt lgkmcnt(6)
	v_mfma_f32_32x32x16_bf16 v[48:63], v[88:91], v[168:171], v[48:63]
	ds_read_b64_tr_b16 v[168:169], v176 offset:20992
	ds_read_b64_tr_b16 v[170:171], v176 offset:23040
	s_waitcnt lgkmcnt(6)
	v_mfma_f32_32x32x16_bf16 v[48:63], v[84:87], v[190:193], v[48:63]
	ds_read_b64_tr_b16 v[190:191], v176 offset:25088
	ds_read_b64_tr_b16 v[192:193], v176 offset:27136
	ds_read_b64_tr_b16 v[200:201], v176 offset:29184
	ds_read_b64_tr_b16 v[202:203], v176 offset:31232
	s_waitcnt lgkmcnt(8)
	v_mfma_f32_32x32x16_bf16 v[48:63], v[80:83], v[194:197], v[48:63]
	s_waitcnt lgkmcnt(6)
	v_mfma_f32_32x32x16_bf16 v[32:47], v[92:95], v[164:167], v[32:47]
	ds_read_b64_tr_b16 v[164:165], v176 offset:17408
	ds_read_b64_tr_b16 v[166:167], v176 offset:19456
	s_waitcnt lgkmcnt(6)
	v_mfma_f32_32x32x16_bf16 v[32:47], v[88:91], v[168:171], v[32:47]
	ds_read_b64_tr_b16 v[168:169], v176 offset:21504
	ds_read_b64_tr_b16 v[170:171], v176 offset:23552
	s_waitcnt lgkmcnt(6)
	v_mfma_f32_32x32x16_bf16 v[32:47], v[84:87], v[190:193], v[32:47]
	ds_read_b64_tr_b16 v[190:191], v176 offset:25600
	ds_read_b64_tr_b16 v[192:193], v176 offset:27648
	ds_read_b64_tr_b16 v[194:195], v176 offset:29696
	ds_read_b64_tr_b16 v[196:197], v176 offset:31744
	s_waitcnt lgkmcnt(8)
	v_mfma_f32_32x32x16_bf16 v[32:47], v[80:83], v[200:203], v[32:47]
	s_waitcnt lgkmcnt(6)
	v_mfma_f32_32x32x16_bf16 v[16:31], v[92:95], v[164:167], v[16:31]
	ds_read_b64_tr_b16 v[164:165], v176 offset:17920
	ds_read_b64_tr_b16 v[166:167], v176 offset:19968
	s_waitcnt lgkmcnt(6)
	v_mfma_f32_32x32x16_bf16 v[16:31], v[88:91], v[168:171], v[16:31]
	ds_read_b64_tr_b16 v[168:169], v176 offset:22016
	ds_read_b64_tr_b16 v[170:171], v176 offset:24064
	s_waitcnt lgkmcnt(6)
	v_mfma_f32_32x32x16_bf16 v[16:31], v[84:87], v[190:193], v[16:31]
	ds_read_b64_tr_b16 v[190:191], v176 offset:26112
	ds_read_b64_tr_b16 v[192:193], v176 offset:28160
	ds_read_b64_tr_b16 v[200:201], v176 offset:30208
	ds_read_b64_tr_b16 v[202:203], v176 offset:32256
	s_waitcnt lgkmcnt(8)
	v_mfma_f32_32x32x16_bf16 v[16:31], v[80:83], v[194:197], v[16:31]
	s_waitcnt lgkmcnt(6)
	v_mfma_f32_32x32x16_bf16 v[0:15], v[92:95], v[164:167], v[0:15]
	s_and_b64 vcc, exec, s[40:41]
	s_waitcnt lgkmcnt(4)
	v_mfma_f32_32x32x16_bf16 v[0:15], v[88:91], v[168:171], v[0:15]
	s_waitcnt lgkmcnt(2)
	v_mfma_f32_32x32x16_bf16 v[0:15], v[84:87], v[190:193], v[0:15]
	s_waitcnt lgkmcnt(0)
	v_mfma_f32_32x32x16_bf16 v[0:15], v[80:83], v[200:203], v[0:15]
	s_cbranch_vccz .LBB0_465
	s_waitcnt vmcnt(0)
	s_barrier
	s_branch .LBB0_460
; #define SBAR() __builtin_amdgcn_sched_barrier(0)
; #define PK4(P, BASE, OUT) do { u32x4 w = {cvtpk(P[BASE + 0], P[BASE + 1]), cvtpk(P[BASE + 2], P[BASE + 3]), cvtpk(P[BASE + 4], P[BASE + 5]), cvtpk(P[BASE + 6], P[BASE + 7])}; \
;     OUT = *reinterpret_cast<bf16x8*>(&w); } while (0)
; #define PUBLISH(n) do { asm volatile("s_waitcnt vmcnt(" #n ")" ::: "memory"); asm volatile("s_waitcnt lgkmcnt(0)" ::: "memory"); __builtin_amdgcn_s_barrier(); SBAR(); } while (0)
; __device__ __forceinline__ void finishSM(f32x16& p0, f32x16& p1, float alpha, float& l_reg, bf16x8& pa0, bf16x8& pa1, bf16x8& pa2, bf16x8& pa3) {
;   for (int r = 0; r < 16; ++r) p1[r] = __builtin_amdgcn_exp2f(p1[r]);
;   float ps = 0; for (int r = 0; r < 16; ++r) ps += p0[r]; for (int r = 0; r < 16; ++r) ps += p1[r];
;   asm volatile("" : "+v"(ps));
;   l_reg = l_reg * alpha + ps;
;     ...
;   PK4(p0, 0, pa0); PK4(p0, 8, pa1); PK4(p1, 0, pa2); PK4(p1, 8, pa3);
;     ...
; }
; __device__ __forceinline__ void qkt(f32x16& p0, f32x16& p1, const bf16* Ks, const bf16x8* qr, int r32, int hi) {
;   p0 = f32x16{}; p1 = f32x16{};
;   for (int d0 = 0; d0 < 8; ++d0) { int cb = (d0 * 16 + hi * 8) * 2;
;     bf16x8 b0 = *reinterpret_cast<const bf16x8*>((const char*)Ks + KSWZ(r32, cb));
;     bf16x8 b1 = *reinterpret_cast<const bf16x8*>((const char*)Ks + KSWZ(32 + r32, cb));
;     p0 = __builtin_amdgcn_mfma_f32_32x32x16_bf16(b0, qr[d0], p0, 0, 0, 0);
;     p1 = __builtin_amdgcn_mfma_f32_32x32x16_bf16(b1, qr[d0], p1, 0, 0, 0); }
; }
; template <typename TQ> ...
;     ...
;   for (int j = 1; j + 1 < NT; j += 2) {
;     SBAR(); qkt(pB0, pB1, (const bf16*)(K_lds + (j & 3) * (int)SHM_K), qr, r32, hi);
;     finishSM(pA0, pA1, alA, l_reg, pa0, pa1, pa2, pa3); SBAR();
;     DMA_TILE(j + 2, (j + 2) & 3); SBAR();
;     pv_d0(o, vb0 + ((j - 1) & 3) * (int)SHM_V, pa0, pa1, pa2, pa3); partialSM<true>(pB0, pB1, m_reg, mnB, alB);
;     PUBLISH(4);
;     SBAR(); qkt(pA0, pA1, (const bf16*)(K_lds + ((j + 1) & 3) * (int)SHM_K), qr, r32, hi);
;     finishSM(pB0, pB1, alB, l_reg, pa0, pa1, pa2, pa3); SBAR();
;     if (j + 3 < NT) { DMA_TILE(j + 3, (j + 3) & 3); } SBAR();
;     pv_d0(o, vb0 + (j & 3) * (int)SHM_V, pa0, pa1, pa2, pa3); partialSM<true>(pA0, pA1, m_reg, mnA, alA);
;     if (j + 3 < NT) { PUBLISH(4); } else { PUBLISH(0); }
.LBB0_465:
	s_waitcnt vmcnt(4)
	s_barrier
	s_branch .LBB0_460
.Lat461_b:
.Lat461_b_in:
	s_mov_b32 s40, s33
	s_addk_i32 s33, 0xc000
	s_and_b32 s42, s33, 0xc000
	s_add_i32 s33, s57, s42
	ds_read_b128 v[80:83], v178 offset:49152
	ds_read_b128 v[84:87], v178 offset:57344
	ds_read_b128 v[198:201], v179 offset:49152
	ds_read_b128 v[202:205], v179 offset:57344
	v_exp_f32_e32 v196, v96
	v_exp_f32_e32 v197, v97
	v_exp_f32_e32 v193, v98
	v_exp_f32_e32 v195, v99
	v_exp_f32_e32 v191, v100
	v_exp_f32_e32 v194, v101
	v_exp_f32_e32 v190, v102
	v_exp_f32_e32 v192, v103
	v_exp_f32_e32 v169, v104
	v_exp_f32_e32 v171, v105
	v_exp_f32_e32 v167, v106
	v_exp_f32_e32 v170, v107
	v_exp_f32_e32 v165, v108
	v_exp_f32_e32 v168, v109
	v_exp_f32_e32 v164, v110
	v_exp_f32_e32 v166, v111
	s_waitcnt lgkmcnt(3)
	v_mfma_f32_32x32x16_bf16 v[96:111], v[80:83], v[136:139], 0
	v_exp_f32_e32 v238, v64
	v_add_f32_e32 v64, v197, v196
	v_add_f32_e32 v64, v193, v64
	v_add_f32_e32 v64, v195, v64
	s_waitcnt lgkmcnt(2)
	v_mfma_f32_32x32x16_bf16 v[80:95], v[84:87], v[136:139], 0
	v_add_f32_e32 v64, v191, v64
	v_add_f32_e32 v64, v194, v64
	v_add_f32_e32 v64, v190, v64
	v_add_f32_e32 v64, v192, v64
	v_add_f32_e32 v64, v169, v64
	v_add_f32_e32 v64, v171, v64
	s_waitcnt lgkmcnt(1)
	v_mfma_f32_32x32x16_bf16 v[96:111], v[198:201], v[140:143], v[96:111]
	v_add_f32_e32 v64, v167, v64
	v_add_f32_e32 v64, v170, v64
	v_add_f32_e32 v64, v165, v64
	v_add_f32_e32 v64, v168, v64
	v_add_f32_e32 v64, v164, v64
	v_add_f32_e32 v64, v166, v64
	v_exp_f32_e32 v239, v68
	s_waitcnt lgkmcnt(0)
	v_mfma_f32_32x32x16_bf16 v[80:95], v[202:205], v[140:143], v[80:95]
	ds_read_b128 v[198:201], v180 offset:49152
	ds_read_b128 v[202:205], v180 offset:57344
	v_add_f32_e32 v64, v238, v64
	v_exp_f32_e32 v240, v69
	v_exp_f32_e32 v241, v70
	v_exp_f32_e32 v242, v71
	s_waitcnt lgkmcnt(1)
	v_mfma_f32_32x32x16_bf16 v[96:111], v[198:201], v[132:135], v[96:111]
	ds_read_b128 v[198:201], v181 offset:49152
	ds_read_b128 v[206:209], v181 offset:57344
	ds_read_b128 v[210:213], v182 offset:49152
	ds_read_b128 v[214:217], v182 offset:57344
	ds_read_b128 v[218:221], v183 offset:49152
	ds_read_b128 v[222:225], v183 offset:57344
	v_exp_f32_e32 v243, v76
	v_exp_f32_e32 v244, v77
	v_exp_f32_e32 v245, v78
	v_exp_f32_e32 v79, v79
	s_waitcnt lgkmcnt(6)
	v_mfma_f32_32x32x16_bf16 v[80:95], v[202:205], v[132:135], v[80:95]
	ds_read_b128 v[202:205], v184 offset:49152
	ds_read_b128 v[226:229], v184 offset:57344
	ds_read_b128 v[230:233], v185 offset:49152
	ds_read_b128 v[234:237], v185 offset:57344
	s_waitcnt lgkmcnt(9)
	v_mfma_f32_32x32x16_bf16 v[96:111], v[198:201], v[128:131], v[96:111]
	v_exp_f32_e32 v199, v65
	v_exp_f32_e32 v200, v66
	v_exp_f32_e32 v201, v67
	v_add_f32_e32 v64, v199, v64
	v_add_f32_e32 v64, v200, v64
	v_add_f32_e32 v64, v201, v64
	s_waitcnt lgkmcnt(8)
	v_mfma_f32_32x32x16_bf16 v[80:95], v[206:209], v[128:131], v[80:95]
	v_exp_f32_e32 v206, v72
	v_add_f32_e32 v64, v239, v64
	v_exp_f32_e32 v207, v73
	v_add_f32_e32 v64, v240, v64
	v_exp_f32_e32 v208, v74
	v_add_f32_e32 v64, v241, v64
	v_exp_f32_e32 v209, v75
	s_waitcnt lgkmcnt(7)
	v_mfma_f32_32x32x16_bf16 v[96:111], v[210:213], v[124:127], v[96:111]
	v_add_f32_e32 v64, v242, v64
	v_add_f32_e32 v64, v206, v64
	v_add_f32_e32 v64, v207, v64
	v_add_f32_e32 v64, v208, v64
	v_add_f32_e32 v64, v209, v64
	v_add_f32_e32 v64, v243, v64
	v_add_f32_e32 v64, v244, v64
	s_waitcnt lgkmcnt(6)
	v_mfma_f32_32x32x16_bf16 v[80:95], v[214:217], v[124:127], v[80:95]
	v_add_f32_e32 v64, v245, v64
	v_add_f32_e32 v198, v79, v64
	v_cvt_pk_bf16_f32 v64, v196, v197
	v_cvt_pk_bf16_f32 v65, v193, v195
	v_cvt_pk_bf16_f32 v66, v191, v194
	v_cvt_pk_bf16_f32 v67, v190, v192
	s_waitcnt lgkmcnt(5)
	v_mfma_f32_32x32x16_bf16 v[96:111], v[218:221], v[120:123], v[96:111]
	v_cvt_pk_bf16_f32 v68, v169, v171
	v_cvt_pk_bf16_f32 v69, v167, v170
	v_cvt_pk_bf16_f32 v70, v165, v168
	v_cvt_pk_bf16_f32 v71, v164, v166
	v_cvt_pk_bf16_f32 v72, v238, v199
	v_cvt_pk_bf16_f32 v73, v200, v201
	v_cvt_pk_bf16_f32 v74, v239, v240
	s_waitcnt lgkmcnt(4)
	v_mfma_f32_32x32x16_bf16 v[80:95], v[222:225], v[120:123], v[80:95]
	v_cvt_pk_bf16_f32 v75, v241, v242
	v_cvt_pk_bf16_f32 v76, v206, v207
	v_cvt_pk_bf16_f32 v77, v208, v209
	v_cvt_pk_bf16_f32 v78, v243, v244
	v_cvt_pk_bf16_f32 v79, v245, v79
	s_waitcnt lgkmcnt(3)
	v_mfma_f32_32x32x16_bf16 v[96:111], v[202:205], v[116:119], v[96:111]
	s_add_i32 s33, s40, 0x8000
	s_and_b32 s43, s33, 0xc000
	ds_read_b64_tr_b16 v[190:191], v176 offset:32768
	ds_read_b64_tr_b16 v[192:193], v176 offset:34816
	ds_read_b64_tr_b16 v[194:195], v176 offset:36864
	ds_read_b64_tr_b16 v[196:197], v176 offset:38912
	s_waitcnt lgkmcnt(6)
	v_mfma_f32_32x32x16_bf16 v[80:95], v[226:229], v[116:119], v[80:95]
	ds_read_b64_tr_b16 v[200:201], v176 offset:40960
	ds_read_b64_tr_b16 v[202:203], v176 offset:43008
	ds_read_b64_tr_b16 v[204:205], v176 offset:45056
	ds_read_b64_tr_b16 v[206:207], v176 offset:47104
	s_add_i32 s74, s40, 0x4000
	s_and_b32 s74, s74, 0xc000
	s_add_u32 s98, s38, s22
	s_addc_u32 s99, s39, s23
	s_add_i32 s41, s67, s74
	s_add_u32 s100, s38, s24
	s_addc_u32 s101, s39, s25
	s_mov_b32 m0, s41
	s_add_i32 s74, s72, s74
	global_load_lds_dwordx4 v156, s[98:99]
	s_waitcnt lgkmcnt(9)
; #define SBAR() __builtin_amdgcn_sched_barrier(0)
; #define PUBLISH(n) do { asm volatile("s_waitcnt vmcnt(" #n ")" ::: "memory"); asm volatile("s_waitcnt lgkmcnt(0)" ::: "memory"); __builtin_amdgcn_s_barrier(); SBAR(); } while (0)
; template <int D0> __device__ __forceinline__ void pv_one(f32x16& od, int vb, bf16x8 pa0, bf16x8 pa1, bf16x8 pa2, bf16x8 pa3) {
;   const s16x4 l0 = tr_read<v_rd_off(D0, 0, 0)>(vb), h0 = tr_read<v_rd_off(D0, 0, 1)>(vb), l1 = tr_read<v_rd_off(D0, 1, 0)>(vb), h1 = tr_read<v_rd_off(D0, 1, 1)>(vb);
;   const s16x4 l2 = tr_read<v_rd_off(D0, 2, 0)>(vb), h2 = tr_read<v_rd_off(D0, 2, 1)>(vb), l3 = tr_read<v_rd_off(D0, 3, 0)>(vb), h3 = tr_read<v_rd_off(D0, 3, 1)>(vb);
;   asm volatile("s_waitcnt lgkmcnt(0)" ::: "memory"); SBAR();
;     ...
;   od = __builtin_amdgcn_mfma_f32_32x32x16_bf16(pa0, PK(l0, h0), od, 0, 0, 0);
;   od = __builtin_amdgcn_mfma_f32_32x32x16_bf16(pa1, PK(l1, h1), od, 0, 0, 0);
;   od = __builtin_amdgcn_mfma_f32_32x32x16_bf16(pa2, PK(l2, h2), od, 0, 0, 0);
;   od = __builtin_amdgcn_mfma_f32_32x32x16_bf16(pa3, PK(l3, h3), od, 0, 0, 0);
;     ...
; }
; __device__ __forceinline__ void pv_d0(f32x16* o, int vb, bf16x8 pa0, bf16x8 pa1, bf16x8 pa2, bf16x8 pa3) {
;   pv_one<0>(o[0], vb, pa0, pa1, pa2, pa3); pv_one<1>(o[1], vb, pa0, pa1, pa2, pa3); pv_one<2>(o[2], vb, pa0, pa1, pa2, pa3); pv_one<3>(o[3], vb, pa0, pa1, pa2, pa3);
; }
; template <typename TQ> ...
;     ...
;   for (int j = 1; j + 1 < NT; j += 2) {
;     SBAR(); qkt(pB0, pB1, (const bf16*)(K_lds + (j & 3) * (int)SHM_K), qr, r32, hi);
;     finishSM(pA0, pA1, alA, l_reg, pa0, pa1, pa2, pa3); SBAR();
;     DMA_TILE(j + 2, (j + 2) & 3); SBAR();
;     pv_d0(o, vb0 + ((j - 1) & 3) * (int)SHM_V, pa0, pa1, pa2, pa3); partialSM<true>(pB0, pB1, m_reg, mnB, alB);
;     PUBLISH(4);
;     SBAR(); qkt(pA0, pA1, (const bf16*)(K_lds + ((j + 1) & 3) * (int)SHM_K), qr, r32, hi);
;     finishSM(pB0, pB1, alB, l_reg, pa0, pa1, pa2, pa3); SBAR();
;     if (j + 3 < NT) { DMA_TILE(j + 3, (j + 3) & 3); } SBAR();
	v_mfma_f32_32x32x16_bf16 v[96:111], v[230:233], v[112:115], v[96:111]
	s_add_i32 m0, s41, 0x2000
	s_nop 0
	global_load_lds_dwordx4 v158, s[98:99]
	s_mov_b32 m0, s74
	s_nop 0
	global_load_lds_dwordx4 v162, s[100:101]
	s_waitcnt lgkmcnt(8)
	v_mfma_f32_32x32x16_bf16 v[80:95], v[234:237], v[112:115], v[80:95]
	s_add_i32 m0, s74, 0x2000
	s_nop 0
	global_load_lds_dwordx4 v160, s[100:101]
	s_nop 0
	s_waitcnt lgkmcnt(6)
	v_mfma_f32_32x32x16_bf16 v[48:63], v[64:67], v[190:193], v[48:63]
	v_exp_f32_e32 v232, v96
	ds_read_b64_tr_b16 v[190:191], v176 offset:33280
	ds_read_b64_tr_b16 v[192:193], v176 offset:35328
	s_waitcnt lgkmcnt(6)
	v_mfma_f32_32x32x16_bf16 v[48:63], v[68:71], v[194:197], v[48:63]
	v_exp_f32_e32 v233, v97
	ds_read_b64_tr_b16 v[194:195], v176 offset:37376
	ds_read_b64_tr_b16 v[196:197], v176 offset:39424
	s_waitcnt lgkmcnt(6)
	v_mfma_f32_32x32x16_bf16 v[48:63], v[72:75], v[200:203], v[48:63]
	v_exp_f32_e32 v234, v98
	ds_read_b64_tr_b16 v[200:201], v176 offset:41472
	ds_read_b64_tr_b16 v[202:203], v176 offset:43520
	ds_read_b64_tr_b16 v[208:209], v176 offset:45568
	ds_read_b64_tr_b16 v[210:211], v176 offset:47616
	s_waitcnt lgkmcnt(8)
	v_mfma_f32_32x32x16_bf16 v[48:63], v[76:79], v[204:207], v[48:63]
	v_exp_f32_e32 v235, v99
	s_waitcnt lgkmcnt(6)
	v_mfma_f32_32x32x16_bf16 v[32:47], v[64:67], v[190:193], v[32:47]
	v_exp_f32_e32 v236, v100
	ds_read_b64_tr_b16 v[190:191], v176 offset:33792
	ds_read_b64_tr_b16 v[192:193], v176 offset:35840
	s_waitcnt lgkmcnt(6)
	v_mfma_f32_32x32x16_bf16 v[32:47], v[68:71], v[194:197], v[32:47]
	v_exp_f32_e32 v237, v101
	ds_read_b64_tr_b16 v[194:195], v176 offset:37888
	ds_read_b64_tr_b16 v[196:197], v176 offset:39936
	s_waitcnt lgkmcnt(6)
	v_mfma_f32_32x32x16_bf16 v[32:47], v[72:75], v[200:203], v[32:47]
	v_exp_f32_e32 v238, v102
	ds_read_b64_tr_b16 v[200:201], v176 offset:41984
	ds_read_b64_tr_b16 v[202:203], v176 offset:44032
	ds_read_b64_tr_b16 v[204:205], v176 offset:46080
	ds_read_b64_tr_b16 v[206:207], v176 offset:48128
	s_waitcnt lgkmcnt(8)
	v_mfma_f32_32x32x16_bf16 v[32:47], v[76:79], v[208:211], v[32:47]
	v_exp_f32_e32 v239, v103
	v_exp_f32_e32 v240, v104
	s_waitcnt lgkmcnt(6)
	v_mfma_f32_32x32x16_bf16 v[16:31], v[64:67], v[190:193], v[16:31]
	v_exp_f32_e32 v241, v105
	ds_read_b64_tr_b16 v[190:191], v176 offset:34304
	ds_read_b64_tr_b16 v[192:193], v176 offset:36352
	s_waitcnt lgkmcnt(6)
	v_mfma_f32_32x32x16_bf16 v[16:31], v[68:71], v[194:197], v[16:31]
	v_exp_f32_e32 v242, v106
	ds_read_b64_tr_b16 v[194:195], v176 offset:38400
	ds_read_b64_tr_b16 v[196:197], v176 offset:40448
	s_waitcnt lgkmcnt(6)
	v_mfma_f32_32x32x16_bf16 v[16:31], v[72:75], v[200:203], v[16:31]
	v_exp_f32_e32 v243, v107
	ds_read_b64_tr_b16 v[200:201], v176 offset:42496
	ds_read_b64_tr_b16 v[202:203], v176 offset:44544
	ds_read_b64_tr_b16 v[208:209], v176 offset:46592
	ds_read_b64_tr_b16 v[210:211], v176 offset:48640
	s_waitcnt lgkmcnt(8)
	v_mfma_f32_32x32x16_bf16 v[16:31], v[76:79], v[204:207], v[16:31]
	v_exp_f32_e32 v244, v108
	s_waitcnt lgkmcnt(6)
	v_mfma_f32_32x32x16_bf16 v[0:15], v[64:67], v[190:193], v[0:15]
	v_exp_f32_e32 v245, v109
	s_waitcnt lgkmcnt(4)
	v_mfma_f32_32x32x16_bf16 v[0:15], v[68:71], v[194:197], v[0:15]
	v_exp_f32_e32 v246, v110
	s_waitcnt lgkmcnt(2)
	v_mfma_f32_32x32x16_bf16 v[0:15], v[72:75], v[200:203], v[0:15]
	v_exp_f32_e32 v247, v111
	s_waitcnt vmcnt(4)
	s_waitcnt lgkmcnt(0)
	s_barrier
	s_and_b32 s40, s40, 0xc000
	s_add_i32 s40, s57, s40
	ds_read_b128 v[64:67], v178
	ds_read_b128 v[68:71], v178 offset:8192
	ds_read_b128 v[190:193], v179
	ds_read_b128 v[194:197], v179 offset:8192
	v_mfma_f32_32x32x16_bf16 v[0:15], v[76:79], v[208:211], v[0:15]
	s_waitcnt lgkmcnt(3)
	v_mfma_f32_32x32x16_bf16 v[96:111], v[64:67], v[136:139], 0
	v_exp_f32_e32 v80, v80
	v_exp_f32_e32 v81, v81
	v_exp_f32_e32 v82, v82
	v_exp_f32_e32 v83, v83
	v_exp_f32_e32 v87, v87
	v_exp_f32_e32 v248, v93
	v_exp_f32_e32 v249, v94
	s_waitcnt lgkmcnt(2)
	v_mfma_f32_32x32x16_bf16 v[64:79], v[68:71], v[136:139], 0
	s_waitcnt lgkmcnt(1)
	v_mfma_f32_32x32x16_bf16 v[96:111], v[190:193], v[140:143], v[96:111]
	s_waitcnt lgkmcnt(0)
	v_mfma_f32_32x32x16_bf16 v[64:79], v[194:197], v[140:143], v[64:79]
	ds_read_b128 v[190:193], v180
	ds_read_b128 v[194:197], v180 offset:8192
	s_waitcnt lgkmcnt(1)
	v_mfma_f32_32x32x16_bf16 v[96:111], v[190:193], v[132:135], v[96:111]
	ds_read_b128 v[190:193], v181
	ds_read_b128 v[200:203], v181 offset:8192
	ds_read_b128 v[204:207], v182
	ds_read_b128 v[208:211], v182 offset:8192
	ds_read_b128 v[212:215], v183
	ds_read_b128 v[216:219], v183 offset:8192
	s_waitcnt lgkmcnt(6)
	v_mfma_f32_32x32x16_bf16 v[64:79], v[194:197], v[132:135], v[64:79]
	ds_read_b128 v[194:197], v184
	ds_read_b128 v[220:223], v184 offset:8192
	ds_read_b128 v[224:227], v185
	ds_read_b128 v[228:231], v185 offset:8192
	s_waitcnt lgkmcnt(9)
	v_mfma_f32_32x32x16_bf16 v[96:111], v[190:193], v[128:131], v[96:111]
	s_cmp_ge_u32 s73, s37
	s_cselect_b64 s[40:41], -1, 0
	s_and_b64 vcc, exec, s[40:41]
	s_cbranch_vccnz .Lat463_b

; __device__ __forceinline__ void finishSM(f32x16& p0, f32x16& p1, float alpha, float& l_reg, bf16x8& pa0, bf16x8& pa1, bf16x8& pa2, bf16x8& pa3) {
;   for (int r = 0; r < 16; ++r) p1[r] = __builtin_amdgcn_exp2f(p1[r]);
;   float ps = 0; for (int r = 0; r < 16; ++r) ps += p0[r]; for (int r = 0; r < 16; ++r) ps += p1[r];
;   asm volatile("" : "+v"(ps));
;   l_reg = l_reg * alpha + ps;
;     ...
;   PK4(p0, 0, pa0); PK4(p0, 8, pa1); PK4(p1, 0, pa2); PK4(p1, 8, pa3);
;     ...
; }
; __device__ __forceinline__ void qkt(f32x16& p0, f32x16& p1, const bf16* Ks, const bf16x8* qr, int r32, int hi) {
;   p0 = f32x16{}; p1 = f32x16{};
;   for (int d0 = 0; d0 < 8; ++d0) { int cb = (d0 * 16 + hi * 8) * 2;
;     bf16x8 b0 = *reinterpret_cast<const bf16x8*>((const char*)Ks + KSWZ(r32, cb));
;     bf16x8 b1 = *reinterpret_cast<const bf16x8*>((const char*)Ks + KSWZ(32 + r32, cb));
;     p0 = __builtin_amdgcn_mfma_f32_32x32x16_bf16(b0, qr[d0], p0, 0, 0, 0);
;     p1 = __builtin_amdgcn_mfma_f32_32x32x16_bf16(b1, qr[d0], p1, 0, 0, 0); }
; }
; __device__ __forceinline__ int v_st(int k, int c) { const int kk = k;
;   return ((kk >> 3) * 4 + (c >> 5)) * 512 + ((kk & 7) * 32 + (c & 31)) * 2; }
; __device__ __forceinline__ int v_rd_base(int lane) { return ((lane & 3) << 3) | (((lane >> 2) & 3) << 6) | (((lane >> 4) & 1) << 5) | (((lane >> 5) & 1) << 8); }
; template <int OFF> __device__ __forceinline__ s16x4 tr_read(int vb) {
;   s16x4 r; asm volatile("ds_read_b64_tr_b16 %0, %1 offset:%2" : "=&v"(r) : "v"(vb), "i"(OFF) : "memory"); return r;
; }
; template <int D0> __device__ __forceinline__ void pv_one(f32x16& od, int vb, bf16x8 pa0, bf16x8 pa1, bf16x8 pa2, bf16x8 pa3) {
;   const s16x4 l0 = tr_read<v_rd_off(D0, 0, 0)>(vb), h0 = tr_read<v_rd_off(D0, 0, 1)>(vb), l1 = tr_read<v_rd_off(D0, 1, 0)>(vb), h1 = tr_read<v_rd_off(D0, 1, 1)>(vb);
;   const s16x4 l2 = tr_read<v_rd_off(D0, 2, 0)>(vb), h2 = tr_read<v_rd_off(D0, 2, 1)>(vb), l3 = tr_read<v_rd_off(D0, 3, 0)>(vb), h3 = tr_read<v_rd_off(D0, 3, 1)>(vb);
;   asm volatile("s_waitcnt lgkmcnt(0)" ::: "memory"); SBAR();
;     ...
;   od = __builtin_amdgcn_mfma_f32_32x32x16_bf16(pa0, PK(l0, h0), od, 0, 0, 0);
;   od = __builtin_amdgcn_mfma_f32_32x32x16_bf16(pa1, PK(l1, h1), od, 0, 0, 0);
;   od = __builtin_amdgcn_mfma_f32_32x32x16_bf16(pa2, PK(l2, h2), od, 0, 0, 0);
;   od = __builtin_amdgcn_mfma_f32_32x32x16_bf16(pa3, PK(l3, h3), od, 0, 0, 0);
;     ...
; }
	s_add_i32 s74, s67, s43
	s_add_u32 s98, s38, s26
	s_addc_u32 s99, s39, s27
	s_mov_b32 m0, s74
	s_add_i32 s43, s72, s43
	global_load_lds_dwordx4 v156, s[98:99]
	s_add_u32 s100, s38, s28
	s_addc_u32 s101, s39, s29
	s_add_i32 m0, s74, 0x2000
	s_nop 0
	global_load_lds_dwordx4 v158, s[98:99]
	s_mov_b32 m0, s43
	s_nop 0
	global_load_lds_dwordx4 v162, s[100:101]
	s_add_i32 m0, s43, 0x2000
	s_nop 0
	global_load_lds_dwordx4 v160, s[100:101]
.Lat463_b:
	v_exp_f32_e32 v190, v84
	v_add_f32_e32 v84, v233, v232
	v_add_f32_e32 v84, v234, v84
	v_add_f32_e32 v84, v235, v84
	v_add_f32_e32 v84, v236, v84
	v_add_f32_e32 v84, v237, v84
	s_waitcnt lgkmcnt(8)
	v_mfma_f32_32x32x16_bf16 v[64:79], v[200:203], v[128:131], v[64:79]
	v_add_f32_e32 v84, v238, v84
	v_add_f32_e32 v84, v239, v84
	v_add_f32_e32 v84, v240, v84
	v_add_f32_e32 v84, v241, v84
	v_add_f32_e32 v84, v242, v84
	v_add_f32_e32 v84, v243, v84
	v_add_f32_e32 v84, v244, v84
	s_waitcnt lgkmcnt(7)
	v_mfma_f32_32x32x16_bf16 v[96:111], v[204:207], v[124:127], v[96:111]
	v_add_f32_e32 v84, v245, v84
	v_add_f32_e32 v84, v246, v84
	v_add_f32_e32 v84, v247, v84
	v_add_f32_e32 v84, v80, v84
	v_exp_f32_e32 v191, v85
	v_add_f32_e32 v84, v81, v84
	v_exp_f32_e32 v192, v86
	s_waitcnt lgkmcnt(6)
	v_mfma_f32_32x32x16_bf16 v[64:79], v[208:211], v[124:127], v[64:79]
	v_add_f32_e32 v84, v82, v84
	v_add_f32_e32 v84, v83, v84
	v_exp_f32_e32 v193, v88
	v_add_f32_e32 v84, v190, v84
	v_exp_f32_e32 v200, v89
	v_add_f32_e32 v84, v191, v84
	v_exp_f32_e32 v201, v90
	s_waitcnt lgkmcnt(5)
	v_mfma_f32_32x32x16_bf16 v[96:111], v[212:215], v[120:123], v[96:111]
	v_add_f32_e32 v84, v192, v84
	v_exp_f32_e32 v202, v91
	v_add_f32_e32 v84, v87, v84
	v_exp_f32_e32 v203, v92
	v_add_f32_e32 v84, v193, v84
	v_add_f32_e32 v84, v200, v84
	v_add_f32_e32 v84, v201, v84
	s_waitcnt lgkmcnt(4)
	v_mfma_f32_32x32x16_bf16 v[64:79], v[216:219], v[120:123], v[64:79]
	v_exp_f32_e32 v204, v95
	v_add_f32_e32 v84, v202, v84
	v_add_f32_e32 v84, v203, v84
	v_add_f32_e32 v84, v248, v84
	v_add_f32_e32 v84, v249, v84
	v_add_f32_e32 v199, v204, v84
	s_waitcnt lgkmcnt(3)
	v_mfma_f32_32x32x16_bf16 v[96:111], v[194:197], v[116:119], v[96:111]
	v_cvt_pk_bf16_f32 v92, v232, v233
	v_cvt_pk_bf16_f32 v93, v234, v235
	v_cvt_pk_bf16_f32 v94, v236, v237
	v_cvt_pk_bf16_f32 v95, v238, v239
	v_cvt_pk_bf16_f32 v88, v240, v241
	v_cvt_pk_bf16_f32 v89, v242, v243
	v_cvt_pk_bf16_f32 v90, v244, v245
	s_waitcnt lgkmcnt(2)
	v_mfma_f32_32x32x16_bf16 v[64:79], v[220:223], v[116:119], v[64:79]
	v_cvt_pk_bf16_f32 v91, v246, v247
	v_cvt_pk_bf16_f32 v84, v80, v81
	v_cvt_pk_bf16_f32 v85, v82, v83
	v_cvt_pk_bf16_f32 v86, v190, v191
	v_cvt_pk_bf16_f32 v87, v192, v87
	v_cvt_pk_bf16_f32 v80, v193, v200
	v_cvt_pk_bf16_f32 v81, v201, v202
	ds_read_b64_tr_b16 v[164:165], v176 offset:49152
	ds_read_b64_tr_b16 v[166:167], v176 offset:51200
	ds_read_b64_tr_b16 v[168:169], v176 offset:53248
	ds_read_b64_tr_b16 v[170:171], v176 offset:55296
	s_waitcnt lgkmcnt(5)
	v_mfma_f32_32x32x16_bf16 v[96:111], v[224:227], v[112:115], v[96:111]
	v_cvt_pk_bf16_f32 v82, v203, v248
	v_cvt_pk_bf16_f32 v83, v249, v204
	ds_read_b64_tr_b16 v[190:191], v176 offset:57344
	ds_read_b64_tr_b16 v[192:193], v176 offset:59392
	ds_read_b64_tr_b16 v[194:195], v176 offset:61440
	ds_read_b64_tr_b16 v[196:197], v176 offset:63488
	s_waitcnt lgkmcnt(8)
	v_mfma_f32_32x32x16_bf16 v[64:79], v[228:231], v[112:115], v[64:79]
	s_nop 0
	s_waitcnt lgkmcnt(6)
	v_mfma_f32_32x32x16_bf16 v[48:63], v[92:95], v[164:167], v[48:63]
	ds_read_b64_tr_b16 v[164:165], v176 offset:49664
	ds_read_b64_tr_b16 v[166:167], v176 offset:51712
	s_waitcnt lgkmcnt(6)
	v_mfma_f32_32x32x16_bf16 v[48:63], v[88:91], v[168:171], v[48:63]
	ds_read_b64_tr_b16 v[168:169], v176 offset:53760
	ds_read_b64_tr_b16 v[170:171], v176 offset:55808
	s_waitcnt lgkmcnt(6)
	v_mfma_f32_32x32x16_bf16 v[48:63], v[84:87], v[190:193], v[48:63]
	ds_read_b64_tr_b16 v[190:191], v176 offset:57856
	ds_read_b64_tr_b16 v[192:193], v176 offset:59904
	ds_read_b64_tr_b16 v[200:201], v176 offset:61952
	ds_read_b64_tr_b16 v[202:203], v176 offset:64000
	s_waitcnt lgkmcnt(8)
	v_mfma_f32_32x32x16_bf16 v[48:63], v[80:83], v[194:197], v[48:63]
	s_waitcnt lgkmcnt(6)
	v_mfma_f32_32x32x16_bf16 v[32:47], v[92:95], v[164:167], v[32:47]
	ds_read_b64_tr_b16 v[164:165], v176 offset:50176
	ds_read_b64_tr_b16 v[166:167], v176 offset:52224
	s_waitcnt lgkmcnt(6)
	v_mfma_f32_32x32x16_bf16 v[32:47], v[88:91], v[168:171], v[32:47]
	ds_read_b64_tr_b16 v[168:169], v176 offset:54272
	ds_read_b64_tr_b16 v[170:171], v176 offset:56320
	s_waitcnt lgkmcnt(6)
	v_mfma_f32_32x32x16_bf16 v[32:47], v[84:87], v[190:193], v[32:47]
	ds_read_b64_tr_b16 v[190:191], v176 offset:58368
	ds_read_b64_tr_b16 v[192:193], v176 offset:60416
	ds_read_b64_tr_b16 v[194:195], v176 offset:62464
	ds_read_b64_tr_b16 v[196:197], v176 offset:64512
	s_waitcnt lgkmcnt(8)
	v_mfma_f32_32x32x16_bf16 v[32:47], v[80:83], v[200:203], v[32:47]
	s_waitcnt lgkmcnt(6)
	v_mfma_f32_32x32x16_bf16 v[16:31], v[92:95], v[164:167], v[16:31]
	ds_read_b64_tr_b16 v[164:165], v176 offset:50688
	ds_read_b64_tr_b16 v[166:167], v176 offset:52736
	s_waitcnt lgkmcnt(6)
	v_mfma_f32_32x32x16_bf16 v[16:31], v[88:91], v[168:171], v[16:31]
	ds_read_b64_tr_b16 v[168:169], v176 offset:54784
	ds_read_b64_tr_b16 v[170:171], v176 offset:56832
	s_waitcnt lgkmcnt(6)
	v_mfma_f32_32x32x16_bf16 v[16:31], v[84:87], v[190:193], v[16:31]
	ds_read_b64_tr_b16 v[190:191], v176 offset:58880
	ds_read_b64_tr_b16 v[192:193], v176 offset:60928
	ds_read_b64_tr_b16 v[200:201], v176 offset:62976
	ds_read_b64_tr_b16 v[202:203], v176 offset:65024
	s_waitcnt lgkmcnt(8)
	v_mfma_f32_32x32x16_bf16 v[16:31], v[80:83], v[194:197], v[16:31]
	s_waitcnt lgkmcnt(6)
	v_mfma_f32_32x32x16_bf16 v[0:15], v[92:95], v[164:167], v[0:15]
	s_and_b64 vcc, exec, s[40:41]
	s_waitcnt lgkmcnt(4)
	v_mfma_f32_32x32x16_bf16 v[0:15], v[88:91], v[168:171], v[0:15]
	s_waitcnt lgkmcnt(2)
	v_mfma_f32_32x32x16_bf16 v[0:15], v[84:87], v[190:193], v[0:15]
	s_waitcnt lgkmcnt(0)
	v_mfma_f32_32x32x16_bf16 v[0:15], v[80:83], v[200:203], v[0:15]
	s_cbranch_vccz .Lat465_b
	s_waitcnt vmcnt(0)
	s_barrier
	s_branch .LBB0_460

; __device__ __forceinline__ void finishSM(f32x16& p0, f32x16& p1, float alpha, float& l_reg, bf16x8& pa0, bf16x8& pa1, bf16x8& pa2, bf16x8& pa3) {
;   for (int r = 0; r < 16; ++r) p1[r] = __builtin_amdgcn_exp2f(p1[r]);
;   float ps = 0; for (int r = 0; r < 16; ++r) ps += p0[r]; for (int r = 0; r < 16; ++r) ps += p1[r];
;   asm volatile("" : "+v"(ps));
;   l_reg = l_reg * alpha + ps;
;     ...
;   PK4(p0, 0, pa0); PK4(p0, 8, pa1); PK4(p1, 0, pa2); PK4(p1, 8, pa3);
;     ...
; }
; __device__ __forceinline__ void qkt(f32x16& p0, f32x16& p1, const bf16* Ks, const bf16x8* qr, int r32, int hi) {
;   p0 = f32x16{}; p1 = f32x16{};
;   for (int d0 = 0; d0 < 8; ++d0) { int cb = (d0 * 16 + hi * 8) * 2;
;     bf16x8 b0 = *reinterpret_cast<const bf16x8*>((const char*)Ks + KSWZ(r32, cb));
;     bf16x8 b1 = *reinterpret_cast<const bf16x8*>((const char*)Ks + KSWZ(32 + r32, cb));
;     p0 = __builtin_amdgcn_mfma_f32_32x32x16_bf16(b0, qr[d0], p0, 0, 0, 0);
;     p1 = __builtin_amdgcn_mfma_f32_32x32x16_bf16(b1, qr[d0], p1, 0, 0, 0); }
; }
; __device__ __forceinline__ int v_st(int k, int c) { const int kk = k;
;   return ((kk >> 3) * 4 + (c >> 5)) * 512 + ((kk & 7) * 32 + (c & 31)) * 2; }
; __device__ __forceinline__ int v_rd_base(int lane) { return ((lane & 3) << 3) | (((lane >> 2) & 3) << 6) | (((lane >> 4) & 1) << 5) | (((lane >> 5) & 1) << 8); }
; template <int OFF> __device__ __forceinline__ s16x4 tr_read(int vb) {
;   s16x4 r; asm volatile("ds_read_b64_tr_b16 %0, %1 offset:%2" : "=&v"(r) : "v"(vb), "i"(OFF) : "memory"); return r;
; }
; template <int D0> __device__ __forceinline__ void pv_one(f32x16& od, int vb, bf16x8 pa0, bf16x8 pa1, bf16x8 pa2, bf16x8 pa3) {
;   const s16x4 l0 = tr_read<v_rd_off(D0, 0, 0)>(vb), h0 = tr_read<v_rd_off(D0, 0, 1)>(vb), l1 = tr_read<v_rd_off(D0, 1, 0)>(vb), h1 = tr_read<v_rd_off(D0, 1, 1)>(vb);
;   const s16x4 l2 = tr_read<v_rd_off(D0, 2, 0)>(vb), h2 = tr_read<v_rd_off(D0, 2, 1)>(vb), l3 = tr_read<v_rd_off(D0, 3, 0)>(vb), h3 = tr_read<v_rd_off(D0, 3, 1)>(vb);
;   asm volatile("s_waitcnt lgkmcnt(0)" ::: "memory"); SBAR();
;     ...
;   od = __builtin_amdgcn_mfma_f32_32x32x16_bf16(pa0, PK(l0, h0), od, 0, 0, 0);
;   od = __builtin_amdgcn_mfma_f32_32x32x16_bf16(pa1, PK(l1, h1), od, 0, 0, 0);
;   od = __builtin_amdgcn_mfma_f32_32x32x16_bf16(pa2, PK(l2, h2), od, 0, 0, 0);
;   od = __builtin_amdgcn_mfma_f32_32x32x16_bf16(pa3, PK(l3, h3), od, 0, 0, 0);
;     ...
; }
.Lat1365_a_go:
	s_waitcnt lgkmcnt(3)
	v_mfma_f32_32x32x16_bf16 v[96:111], v[80:83], v[136:139], 0
	v_exp_f32_e32 v238, v64
	v_add_f32_e32 v64, v197, v196
	v_add_f32_e32 v64, v193, v64
	v_add_f32_e32 v64, v195, v64
	s_waitcnt lgkmcnt(2)
	v_mfma_f32_32x32x16_bf16 v[80:95], v[84:87], v[136:139], 0
	v_add_f32_e32 v64, v191, v64
	v_add_f32_e32 v64, v194, v64
	v_add_f32_e32 v64, v190, v64
	v_add_f32_e32 v64, v192, v64
	v_add_f32_e32 v64, v169, v64
	v_add_f32_e32 v64, v171, v64
	s_waitcnt lgkmcnt(1)
	v_mfma_f32_32x32x16_bf16 v[96:111], v[198:201], v[140:143], v[96:111]
	v_add_f32_e32 v64, v167, v64
	v_add_f32_e32 v64, v170, v64
	v_add_f32_e32 v64, v165, v64
	v_add_f32_e32 v64, v168, v64
	v_add_f32_e32 v64, v164, v64
	v_add_f32_e32 v64, v166, v64
	v_exp_f32_e32 v239, v68
	s_waitcnt lgkmcnt(0)
	v_mfma_f32_32x32x16_bf16 v[80:95], v[202:205], v[140:143], v[80:95]
	ds_read_b128 v[198:201], v180 offset:16384
	ds_read_b128 v[202:205], v180 offset:24576
	v_add_f32_e32 v64, v238, v64
	v_exp_f32_e32 v240, v69
	v_exp_f32_e32 v241, v70
	v_exp_f32_e32 v242, v71
	s_waitcnt lgkmcnt(1)
	v_mfma_f32_32x32x16_bf16 v[96:111], v[198:201], v[132:135], v[96:111]
	ds_read_b128 v[198:201], v181 offset:16384
	ds_read_b128 v[206:209], v181 offset:24576
	ds_read_b128 v[210:213], v182 offset:16384
	ds_read_b128 v[214:217], v182 offset:24576
	ds_read_b128 v[218:221], v183 offset:16384
	ds_read_b128 v[222:225], v183 offset:24576
	v_exp_f32_e32 v243, v76
	v_exp_f32_e32 v244, v77
	v_exp_f32_e32 v245, v78
	v_exp_f32_e32 v79, v79
	s_waitcnt lgkmcnt(6)
	v_mfma_f32_32x32x16_bf16 v[80:95], v[202:205], v[132:135], v[80:95]
	ds_read_b128 v[202:205], v184 offset:16384
	ds_read_b128 v[226:229], v184 offset:24576
	ds_read_b128 v[230:233], v185 offset:16384
	ds_read_b128 v[234:237], v185 offset:24576
	s_waitcnt lgkmcnt(9)
	v_mfma_f32_32x32x16_bf16 v[96:111], v[198:201], v[128:131], v[96:111]
	v_exp_f32_e32 v199, v65
	v_exp_f32_e32 v200, v66
	v_exp_f32_e32 v201, v67
	v_add_f32_e32 v64, v199, v64
	v_add_f32_e32 v64, v200, v64
	v_add_f32_e32 v64, v201, v64
	s_waitcnt lgkmcnt(8)
	v_mfma_f32_32x32x16_bf16 v[80:95], v[206:209], v[128:131], v[80:95]
	v_exp_f32_e32 v206, v72
	v_add_f32_e32 v64, v239, v64
	v_exp_f32_e32 v207, v73
	v_add_f32_e32 v64, v240, v64
	v_exp_f32_e32 v208, v74
	v_add_f32_e32 v64, v241, v64
	v_exp_f32_e32 v209, v75
	s_waitcnt lgkmcnt(7)
	v_mfma_f32_32x32x16_bf16 v[96:111], v[210:213], v[124:127], v[96:111]
	v_add_f32_e32 v64, v242, v64
	v_add_f32_e32 v64, v206, v64
	v_add_f32_e32 v64, v207, v64
	v_add_f32_e32 v64, v208, v64
	v_add_f32_e32 v64, v209, v64
	v_add_f32_e32 v64, v243, v64
	v_add_f32_e32 v64, v244, v64
	s_waitcnt lgkmcnt(6)
	v_mfma_f32_32x32x16_bf16 v[80:95], v[214:217], v[124:127], v[80:95]
	v_add_f32_e32 v64, v245, v64
	v_add_f32_e32 v198, v79, v64
	v_cvt_pk_bf16_f32 v64, v196, v197
	v_cvt_pk_bf16_f32 v65, v193, v195
	v_cvt_pk_bf16_f32 v66, v191, v194
	v_cvt_pk_bf16_f32 v67, v190, v192
	s_waitcnt lgkmcnt(5)
	v_mfma_f32_32x32x16_bf16 v[96:111], v[218:221], v[120:123], v[96:111]
	v_cvt_pk_bf16_f32 v68, v169, v171
	v_cvt_pk_bf16_f32 v69, v167, v170
	v_cvt_pk_bf16_f32 v70, v165, v168
	v_cvt_pk_bf16_f32 v71, v164, v166
	v_cvt_pk_bf16_f32 v72, v238, v199
	v_cvt_pk_bf16_f32 v73, v200, v201
	v_cvt_pk_bf16_f32 v74, v239, v240
	s_waitcnt lgkmcnt(4)
	v_mfma_f32_32x32x16_bf16 v[80:95], v[222:225], v[120:123], v[80:95]
	v_cvt_pk_bf16_f32 v75, v241, v242
	v_cvt_pk_bf16_f32 v76, v206, v207
	v_cvt_pk_bf16_f32 v77, v208, v209
	v_cvt_pk_bf16_f32 v78, v243, v244
	v_cvt_pk_bf16_f32 v79, v245, v79
	s_waitcnt lgkmcnt(3)
	v_mfma_f32_32x32x16_bf16 v[96:111], v[202:205], v[116:119], v[96:111]
	s_add_i32 s33, s40, 0x8000
	s_and_b32 s43, s33, 0xc000
	ds_read_b64_tr_b16 v[190:191], v176
	ds_read_b64_tr_b16 v[192:193], v176 offset:2048
	ds_read_b64_tr_b16 v[194:195], v176 offset:4096
	ds_read_b64_tr_b16 v[196:197], v176 offset:6144
	s_waitcnt lgkmcnt(6)
	v_mfma_f32_32x32x16_bf16 v[80:95], v[226:229], v[116:119], v[80:95]
	ds_read_b64_tr_b16 v[200:201], v176 offset:8192
	ds_read_b64_tr_b16 v[202:203], v176 offset:10240
	ds_read_b64_tr_b16 v[204:205], v176 offset:12288
	ds_read_b64_tr_b16 v[206:207], v176 offset:14336
	s_add_i32 s73, s40, 0x4000
	s_and_b32 s73, s73, 0xc000
	s_add_u32 s98, s38, s22
	s_addc_u32 s99, s39, s23
	s_add_i32 s41, s66, s73
	s_add_u32 s100, s38, s24
	s_addc_u32 s101, s39, s25
	s_mov_b32 m0, s41
	s_add_i32 s73, s67, s73
	global_load_lds_dwordx4 v156, s[98:99]
	s_waitcnt lgkmcnt(9)
	v_mfma_f32_32x32x16_bf16 v[96:111], v[230:233], v[112:115], v[96:111]
	s_add_i32 m0, s41, 0x2000
	s_nop 0
	global_load_lds_dwordx4 v158, s[98:99]
	s_mov_b32 m0, s73
	s_nop 0
	global_load_lds_dwordx4 v162, s[100:101]
	s_waitcnt lgkmcnt(8)
	v_mfma_f32_32x32x16_bf16 v[80:95], v[234:237], v[112:115], v[80:95]
	s_add_i32 m0, s73, 0x2000
	s_nop 0
	global_load_lds_dwordx4 v160, s[100:101]
	s_nop 0
	s_waitcnt lgkmcnt(6)
	v_mfma_f32_32x32x16_bf16 v[48:63], v[64:67], v[190:193], v[48:63]
	v_exp_f32_e32 v232, v96
	ds_read_b64_tr_b16 v[190:191], v176 offset:512
	ds_read_b64_tr_b16 v[192:193], v176 offset:2560
	s_waitcnt lgkmcnt(6)
; #define SBAR() __builtin_amdgcn_sched_barrier(0)
; #define PUBLISH(n) do { asm volatile("s_waitcnt vmcnt(" #n ")" ::: "memory"); asm volatile("s_waitcnt lgkmcnt(0)" ::: "memory"); __builtin_amdgcn_s_barrier(); SBAR(); } while (0)
; template <int D0> __device__ __forceinline__ void pv_one(f32x16& od, int vb, bf16x8 pa0, bf16x8 pa1, bf16x8 pa2, bf16x8 pa3) {
;   const s16x4 l0 = tr_read<v_rd_off(D0, 0, 0)>(vb), h0 = tr_read<v_rd_off(D0, 0, 1)>(vb), l1 = tr_read<v_rd_off(D0, 1, 0)>(vb), h1 = tr_read<v_rd_off(D0, 1, 1)>(vb);
;   const s16x4 l2 = tr_read<v_rd_off(D0, 2, 0)>(vb), h2 = tr_read<v_rd_off(D0, 2, 1)>(vb), l3 = tr_read<v_rd_off(D0, 3, 0)>(vb), h3 = tr_read<v_rd_off(D0, 3, 1)>(vb);
;   asm volatile("s_waitcnt lgkmcnt(0)" ::: "memory"); SBAR();
;     ...
;   od = __builtin_amdgcn_mfma_f32_32x32x16_bf16(pa0, PK(l0, h0), od, 0, 0, 0);
;   od = __builtin_amdgcn_mfma_f32_32x32x16_bf16(pa1, PK(l1, h1), od, 0, 0, 0);
;   od = __builtin_amdgcn_mfma_f32_32x32x16_bf16(pa2, PK(l2, h2), od, 0, 0, 0);
;   od = __builtin_amdgcn_mfma_f32_32x32x16_bf16(pa3, PK(l3, h3), od, 0, 0, 0);
;     ...
; }
; __device__ __forceinline__ void pv_d0(f32x16* o, int vb, bf16x8 pa0, bf16x8 pa1, bf16x8 pa2, bf16x8 pa3) {
;   pv_one<0>(o[0], vb, pa0, pa1, pa2, pa3); pv_one<1>(o[1], vb, pa0, pa1, pa2, pa3); pv_one<2>(o[2], vb, pa0, pa1, pa2, pa3); pv_one<3>(o[3], vb, pa0, pa1, pa2, pa3);
; }
; template <typename TQ> ...
;     ...
;   for (int j = 1; j + 1 < NT; j += 2) {
;     SBAR(); qkt(pB0, pB1, (const bf16*)(K_lds + (j & 3) * (int)SHM_K), qr, r32, hi);
;     finishSM(pA0, pA1, alA, l_reg, pa0, pa1, pa2, pa3); SBAR();
;     DMA_TILE(j + 2, (j + 2) & 3); SBAR();
;     pv_d0(o, vb0 + ((j - 1) & 3) * (int)SHM_V, pa0, pa1, pa2, pa3); partialSM<true>(pB0, pB1, m_reg, mnB, alB);
;     PUBLISH(4);
;     SBAR(); qkt(pA0, pA1, (const bf16*)(K_lds + ((j + 1) & 3) * (int)SHM_K), qr, r32, hi);
;     finishSM(pB0, pB1, alB, l_reg, pa0, pa1, pa2, pa3); SBAR();
;     if (j + 3 < NT) { DMA_TILE(j + 3, (j + 3) & 3); } SBAR();
	v_mfma_f32_32x32x16_bf16 v[48:63], v[68:71], v[194:197], v[48:63]
	v_exp_f32_e32 v233, v97
	ds_read_b64_tr_b16 v[194:195], v176 offset:4608
	ds_read_b64_tr_b16 v[196:197], v176 offset:6656
	s_waitcnt lgkmcnt(6)
	v_mfma_f32_32x32x16_bf16 v[48:63], v[72:75], v[200:203], v[48:63]
	v_exp_f32_e32 v234, v98
	ds_read_b64_tr_b16 v[200:201], v176 offset:8704
	ds_read_b64_tr_b16 v[202:203], v176 offset:10752
	ds_read_b64_tr_b16 v[208:209], v176 offset:12800
	ds_read_b64_tr_b16 v[210:211], v176 offset:14848
	s_waitcnt lgkmcnt(8)
	v_mfma_f32_32x32x16_bf16 v[48:63], v[76:79], v[204:207], v[48:63]
	v_exp_f32_e32 v235, v99
	s_waitcnt lgkmcnt(6)
	v_mfma_f32_32x32x16_bf16 v[32:47], v[64:67], v[190:193], v[32:47]
	v_exp_f32_e32 v236, v100
	ds_read_b64_tr_b16 v[190:191], v176 offset:1024
	ds_read_b64_tr_b16 v[192:193], v176 offset:3072
	s_waitcnt lgkmcnt(6)
	v_mfma_f32_32x32x16_bf16 v[32:47], v[68:71], v[194:197], v[32:47]
	v_exp_f32_e32 v237, v101
	ds_read_b64_tr_b16 v[194:195], v176 offset:5120
	ds_read_b64_tr_b16 v[196:197], v176 offset:7168
	s_waitcnt lgkmcnt(6)
	v_mfma_f32_32x32x16_bf16 v[32:47], v[72:75], v[200:203], v[32:47]
	v_exp_f32_e32 v238, v102
	ds_read_b64_tr_b16 v[200:201], v176 offset:9216
	ds_read_b64_tr_b16 v[202:203], v176 offset:11264
	ds_read_b64_tr_b16 v[204:205], v176 offset:13312
	ds_read_b64_tr_b16 v[206:207], v176 offset:15360
	s_waitcnt lgkmcnt(8)
	v_mfma_f32_32x32x16_bf16 v[32:47], v[76:79], v[208:211], v[32:47]
	v_exp_f32_e32 v239, v103
	v_exp_f32_e32 v240, v104
	s_waitcnt lgkmcnt(6)
	v_mfma_f32_32x32x16_bf16 v[16:31], v[64:67], v[190:193], v[16:31]
	v_exp_f32_e32 v241, v105
	ds_read_b64_tr_b16 v[190:191], v176 offset:1536
	ds_read_b64_tr_b16 v[192:193], v176 offset:3584
	s_waitcnt lgkmcnt(6)
	v_mfma_f32_32x32x16_bf16 v[16:31], v[68:71], v[194:197], v[16:31]
	v_exp_f32_e32 v242, v106
	ds_read_b64_tr_b16 v[194:195], v176 offset:5632
	ds_read_b64_tr_b16 v[196:197], v176 offset:7680
	s_waitcnt lgkmcnt(6)
	v_mfma_f32_32x32x16_bf16 v[16:31], v[72:75], v[200:203], v[16:31]
	v_exp_f32_e32 v243, v107
	ds_read_b64_tr_b16 v[200:201], v176 offset:9728
	ds_read_b64_tr_b16 v[202:203], v176 offset:11776
	ds_read_b64_tr_b16 v[208:209], v176 offset:13824
	ds_read_b64_tr_b16 v[210:211], v176 offset:15872
	s_waitcnt lgkmcnt(8)
	v_mfma_f32_32x32x16_bf16 v[16:31], v[76:79], v[204:207], v[16:31]
	v_exp_f32_e32 v244, v108
	s_waitcnt lgkmcnt(6)
	v_mfma_f32_32x32x16_bf16 v[0:15], v[64:67], v[190:193], v[0:15]
	v_exp_f32_e32 v245, v109
	s_waitcnt lgkmcnt(4)
	v_mfma_f32_32x32x16_bf16 v[0:15], v[68:71], v[194:197], v[0:15]
	v_exp_f32_e32 v246, v110
	s_waitcnt lgkmcnt(2)
	v_mfma_f32_32x32x16_bf16 v[0:15], v[72:75], v[200:203], v[0:15]
	v_exp_f32_e32 v247, v111
	s_waitcnt vmcnt(4)
	s_waitcnt lgkmcnt(0)
	s_barrier
	s_and_b32 s40, s40, 0xc000
	s_add_i32 s40, s56, s40
	ds_read_b128 v[64:67], v178 offset:32768
	ds_read_b128 v[68:71], v178 offset:40960
	ds_read_b128 v[190:193], v179 offset:32768
	ds_read_b128 v[194:197], v179 offset:40960
	v_mfma_f32_32x32x16_bf16 v[0:15], v[76:79], v[208:211], v[0:15]
	s_waitcnt lgkmcnt(3)
	v_mfma_f32_32x32x16_bf16 v[96:111], v[64:67], v[136:139], 0
	v_exp_f32_e32 v80, v80
	v_exp_f32_e32 v81, v81
	v_exp_f32_e32 v82, v82
	v_exp_f32_e32 v83, v83
	v_exp_f32_e32 v87, v87
	v_exp_f32_e32 v248, v93
	v_exp_f32_e32 v249, v94
	s_waitcnt lgkmcnt(2)
	v_mfma_f32_32x32x16_bf16 v[64:79], v[68:71], v[136:139], 0
	s_waitcnt lgkmcnt(1)
	v_mfma_f32_32x32x16_bf16 v[96:111], v[190:193], v[140:143], v[96:111]
	s_waitcnt lgkmcnt(0)
	v_mfma_f32_32x32x16_bf16 v[64:79], v[194:197], v[140:143], v[64:79]
	ds_read_b128 v[190:193], v180 offset:32768
	ds_read_b128 v[194:197], v180 offset:40960
	s_waitcnt lgkmcnt(1)
	v_mfma_f32_32x32x16_bf16 v[96:111], v[190:193], v[132:135], v[96:111]
	ds_read_b128 v[190:193], v181 offset:32768
	ds_read_b128 v[200:203], v181 offset:40960
	ds_read_b128 v[204:207], v182 offset:32768
	ds_read_b128 v[208:211], v182 offset:40960
	ds_read_b128 v[212:215], v183 offset:32768
	ds_read_b128 v[216:219], v183 offset:40960
	s_waitcnt lgkmcnt(6)
	v_mfma_f32_32x32x16_bf16 v[64:79], v[194:197], v[132:135], v[64:79]
	ds_read_b128 v[194:197], v184 offset:32768
	ds_read_b128 v[220:223], v184 offset:40960
	ds_read_b128 v[224:227], v185 offset:32768
	ds_read_b128 v[228:231], v185 offset:40960
	s_waitcnt lgkmcnt(9)
	v_mfma_f32_32x32x16_bf16 v[96:111], v[190:193], v[128:131], v[96:111]
	s_cmp_ge_u32 s72, s37
	s_cselect_b64 s[40:41], -1, 0
	s_and_b64 vcc, exec, s[40:41]
	s_cbranch_vccnz .LBB0_1367
	s_add_i32 s73, s66, s43
	s_add_u32 s98, s38, s26
	s_addc_u32 s99, s39, s27
	s_mov_b32 m0, s73
	s_add_i32 s43, s67, s43
	global_load_lds_dwordx4 v156, s[98:99]
	s_add_u32 s100, s38, s28
	s_addc_u32 s101, s39, s29
	s_add_i32 m0, s73, 0x2000
	s_nop 0
	global_load_lds_dwordx4 v158, s[98:99]
	s_mov_b32 m0, s43
	s_nop 0
	global_load_lds_dwordx4 v162, s[100:101]
	s_add_i32 m0, s43, 0x2000
	s_nop 0
	global_load_lds_dwordx4 v160, s[100:101]

; #define SBAR() __builtin_amdgcn_sched_barrier(0)
; #define PK4(P, BASE, OUT) do { u32x4 w = {cvtpk(P[BASE + 0], P[BASE + 1]), cvtpk(P[BASE + 2], P[BASE + 3]), cvtpk(P[BASE + 4], P[BASE + 5]), cvtpk(P[BASE + 6], P[BASE + 7])}; \
;     OUT = *reinterpret_cast<bf16x8*>(&w); } while (0)
; __device__ __forceinline__ void finishSM(f32x16& p0, f32x16& p1, float alpha, float& l_reg, bf16x8& pa0, bf16x8& pa1, bf16x8& pa2, bf16x8& pa3) {
;   for (int r = 0; r < 16; ++r) p1[r] = __builtin_amdgcn_exp2f(p1[r]);
;   float ps = 0; for (int r = 0; r < 16; ++r) ps += p0[r]; for (int r = 0; r < 16; ++r) ps += p1[r];
;   asm volatile("" : "+v"(ps));
;   l_reg = l_reg * alpha + ps;
;     ...
;   PK4(p0, 0, pa0); PK4(p0, 8, pa1); PK4(p1, 0, pa2); PK4(p1, 8, pa3);
;     ...
; }
; __device__ __forceinline__ void qkt(f32x16& p0, f32x16& p1, const bf16* Ks, const bf16x8* qr, int r32, int hi) {
;   p0 = f32x16{}; p1 = f32x16{};
;   for (int d0 = 0; d0 < 8; ++d0) { int cb = (d0 * 16 + hi * 8) * 2;
;     bf16x8 b0 = *reinterpret_cast<const bf16x8*>((const char*)Ks + KSWZ(r32, cb));
;     bf16x8 b1 = *reinterpret_cast<const bf16x8*>((const char*)Ks + KSWZ(32 + r32, cb));
;     p0 = __builtin_amdgcn_mfma_f32_32x32x16_bf16(b0, qr[d0], p0, 0, 0, 0);
;     p1 = __builtin_amdgcn_mfma_f32_32x32x16_bf16(b1, qr[d0], p1, 0, 0, 0); }
; }
; template <typename TQ> ...
;     ...
;   for (int j = 1; j + 1 < NT; j += 2) {
;     SBAR(); qkt(pB0, pB1, (const bf16*)(K_lds + (j & 3) * (int)SHM_K), qr, r32, hi);
;     finishSM(pA0, pA1, alA, l_reg, pa0, pa1, pa2, pa3); SBAR();
;     DMA_TILE(j + 2, (j + 2) & 3); SBAR();
;     pv_d0(o, vb0 + ((j - 1) & 3) * (int)SHM_V, pa0, pa1, pa2, pa3); partialSM<true>(pB0, pB1, m_reg, mnB, alB);
.Lat1365_b:
.Lat1365_b_in:
	s_mov_b32 s40, s33
	s_addk_i32 s33, 0xc000
	s_and_b32 s42, s33, 0xc000
	s_add_i32 s33, s56, s42
	ds_read_b128 v[80:83], v178 offset:49152
	ds_read_b128 v[84:87], v178 offset:57344
	ds_read_b128 v[198:201], v179 offset:49152
	ds_read_b128 v[202:205], v179 offset:57344
	v_exp_f32_e32 v196, v96
	v_exp_f32_e32 v197, v97
	v_exp_f32_e32 v193, v98
	v_exp_f32_e32 v195, v99
	v_exp_f32_e32 v191, v100
	v_exp_f32_e32 v194, v101
	v_exp_f32_e32 v190, v102
	v_exp_f32_e32 v192, v103
	v_exp_f32_e32 v169, v104
	v_exp_f32_e32 v171, v105
	v_exp_f32_e32 v167, v106
	v_exp_f32_e32 v170, v107
	v_exp_f32_e32 v165, v108
	v_exp_f32_e32 v168, v109
	v_exp_f32_e32 v164, v110
	v_exp_f32_e32 v166, v111
	s_waitcnt lgkmcnt(3)
	v_mfma_f32_32x32x16_bf16 v[96:111], v[80:83], v[136:139], 0
	v_exp_f32_e32 v238, v64
	v_add_f32_e32 v64, v197, v196
	v_add_f32_e32 v64, v193, v64
	v_add_f32_e32 v64, v195, v64
	s_waitcnt lgkmcnt(2)
	v_mfma_f32_32x32x16_bf16 v[80:95], v[84:87], v[136:139], 0
	v_add_f32_e32 v64, v191, v64
	v_add_f32_e32 v64, v194, v64
	v_add_f32_e32 v64, v190, v64
	v_add_f32_e32 v64, v192, v64
	v_add_f32_e32 v64, v169, v64
	v_add_f32_e32 v64, v171, v64
	s_waitcnt lgkmcnt(1)
	v_mfma_f32_32x32x16_bf16 v[96:111], v[198:201], v[140:143], v[96:111]
	v_add_f32_e32 v64, v167, v64
	v_add_f32_e32 v64, v170, v64
	v_add_f32_e32 v64, v165, v64
	v_add_f32_e32 v64, v168, v64
	v_add_f32_e32 v64, v164, v64
	v_add_f32_e32 v64, v166, v64
	v_exp_f32_e32 v239, v68
	s_waitcnt lgkmcnt(0)
	v_mfma_f32_32x32x16_bf16 v[80:95], v[202:205], v[140:143], v[80:95]
	ds_read_b128 v[198:201], v180 offset:49152
	ds_read_b128 v[202:205], v180 offset:57344
	v_add_f32_e32 v64, v238, v64
	v_exp_f32_e32 v240, v69
	v_exp_f32_e32 v241, v70
	v_exp_f32_e32 v242, v71
	s_waitcnt lgkmcnt(1)
	v_mfma_f32_32x32x16_bf16 v[96:111], v[198:201], v[132:135], v[96:111]
	ds_read_b128 v[198:201], v181 offset:49152
	ds_read_b128 v[206:209], v181 offset:57344
	ds_read_b128 v[210:213], v182 offset:49152
	ds_read_b128 v[214:217], v182 offset:57344
	ds_read_b128 v[218:221], v183 offset:49152
	ds_read_b128 v[222:225], v183 offset:57344
	v_exp_f32_e32 v243, v76
	v_exp_f32_e32 v244, v77
	v_exp_f32_e32 v245, v78
	v_exp_f32_e32 v79, v79
	s_waitcnt lgkmcnt(6)
	v_mfma_f32_32x32x16_bf16 v[80:95], v[202:205], v[132:135], v[80:95]
	ds_read_b128 v[202:205], v184 offset:49152
	ds_read_b128 v[226:229], v184 offset:57344
	ds_read_b128 v[230:233], v185 offset:49152
	ds_read_b128 v[234:237], v185 offset:57344
	s_waitcnt lgkmcnt(9)
	v_mfma_f32_32x32x16_bf16 v[96:111], v[198:201], v[128:131], v[96:111]
	v_exp_f32_e32 v199, v65
	v_exp_f32_e32 v200, v66
	v_exp_f32_e32 v201, v67
	v_add_f32_e32 v64, v199, v64
	v_add_f32_e32 v64, v200, v64
	v_add_f32_e32 v64, v201, v64
	s_waitcnt lgkmcnt(8)
	v_mfma_f32_32x32x16_bf16 v[80:95], v[206:209], v[128:131], v[80:95]
	v_exp_f32_e32 v206, v72
	v_add_f32_e32 v64, v239, v64
	v_exp_f32_e32 v207, v73
	v_add_f32_e32 v64, v240, v64
	v_exp_f32_e32 v208, v74
	v_add_f32_e32 v64, v241, v64
	v_exp_f32_e32 v209, v75
	s_waitcnt lgkmcnt(7)
	v_mfma_f32_32x32x16_bf16 v[96:111], v[210:213], v[124:127], v[96:111]
	v_add_f32_e32 v64, v242, v64
	v_add_f32_e32 v64, v206, v64
	v_add_f32_e32 v64, v207, v64
	v_add_f32_e32 v64, v208, v64
	v_add_f32_e32 v64, v209, v64
	v_add_f32_e32 v64, v243, v64
	v_add_f32_e32 v64, v244, v64
	s_waitcnt lgkmcnt(6)
	v_mfma_f32_32x32x16_bf16 v[80:95], v[214:217], v[124:127], v[80:95]
	v_add_f32_e32 v64, v245, v64
	v_add_f32_e32 v198, v79, v64
	v_cvt_pk_bf16_f32 v64, v196, v197
	v_cvt_pk_bf16_f32 v65, v193, v195
	v_cvt_pk_bf16_f32 v66, v191, v194
	v_cvt_pk_bf16_f32 v67, v190, v192
	s_waitcnt lgkmcnt(5)
	v_mfma_f32_32x32x16_bf16 v[96:111], v[218:221], v[120:123], v[96:111]
	v_cvt_pk_bf16_f32 v68, v169, v171
	v_cvt_pk_bf16_f32 v69, v167, v170
	v_cvt_pk_bf16_f32 v70, v165, v168
	v_cvt_pk_bf16_f32 v71, v164, v166
	v_cvt_pk_bf16_f32 v72, v238, v199
	v_cvt_pk_bf16_f32 v73, v200, v201
	v_cvt_pk_bf16_f32 v74, v239, v240
	s_waitcnt lgkmcnt(4)
	v_mfma_f32_32x32x16_bf16 v[80:95], v[222:225], v[120:123], v[80:95]
	v_cvt_pk_bf16_f32 v75, v241, v242
	v_cvt_pk_bf16_f32 v76, v206, v207
	v_cvt_pk_bf16_f32 v77, v208, v209
	v_cvt_pk_bf16_f32 v78, v243, v244
	v_cvt_pk_bf16_f32 v79, v245, v79
	s_waitcnt lgkmcnt(3)
	v_mfma_f32_32x32x16_bf16 v[96:111], v[202:205], v[116:119], v[96:111]
	s_add_i32 s33, s40, 0x8000
	s_and_b32 s43, s33, 0xc000
	ds_read_b64_tr_b16 v[190:191], v176 offset:32768
	ds_read_b64_tr_b16 v[192:193], v176 offset:34816
	ds_read_b64_tr_b16 v[194:195], v176 offset:36864
	ds_read_b64_tr_b16 v[196:197], v176 offset:38912
	s_waitcnt lgkmcnt(6)
	v_mfma_f32_32x32x16_bf16 v[80:95], v[226:229], v[116:119], v[80:95]
	ds_read_b64_tr_b16 v[200:201], v176 offset:40960
	ds_read_b64_tr_b16 v[202:203], v176 offset:43008
	ds_read_b64_tr_b16 v[204:205], v176 offset:45056
	ds_read_b64_tr_b16 v[206:207], v176 offset:47104
	s_add_i32 s73, s40, 0x4000
	s_and_b32 s73, s73, 0xc000
	s_add_u32 s98, s38, s22
	s_addc_u32 s99, s39, s23
	s_add_i32 s41, s66, s73
	s_add_u32 s100, s38, s24
	s_addc_u32 s101, s39, s25
	s_mov_b32 m0, s41
	s_add_i32 s73, s67, s73
	global_load_lds_dwordx4 v156, s[98:99]
	s_waitcnt lgkmcnt(9)
; #define SBAR() __builtin_amdgcn_sched_barrier(0)
; #define PUBLISH(n) do { asm volatile("s_waitcnt vmcnt(" #n ")" ::: "memory"); asm volatile("s_waitcnt lgkmcnt(0)" ::: "memory"); __builtin_amdgcn_s_barrier(); SBAR(); } while (0)
; template <int D0> __device__ __forceinline__ void pv_one(f32x16& od, int vb, bf16x8 pa0, bf16x8 pa1, bf16x8 pa2, bf16x8 pa3) {
;   const s16x4 l0 = tr_read<v_rd_off(D0, 0, 0)>(vb), h0 = tr_read<v_rd_off(D0, 0, 1)>(vb), l1 = tr_read<v_rd_off(D0, 1, 0)>(vb), h1 = tr_read<v_rd_off(D0, 1, 1)>(vb);
;   const s16x4 l2 = tr_read<v_rd_off(D0, 2, 0)>(vb), h2 = tr_read<v_rd_off(D0, 2, 1)>(vb), l3 = tr_read<v_rd_off(D0, 3, 0)>(vb), h3 = tr_read<v_rd_off(D0, 3, 1)>(vb);
;   asm volatile("s_waitcnt lgkmcnt(0)" ::: "memory"); SBAR();
;     ...
;   od = __builtin_amdgcn_mfma_f32_32x32x16_bf16(pa0, PK(l0, h0), od, 0, 0, 0);
;   od = __builtin_amdgcn_mfma_f32_32x32x16_bf16(pa1, PK(l1, h1), od, 0, 0, 0);
;   od = __builtin_amdgcn_mfma_f32_32x32x16_bf16(pa2, PK(l2, h2), od, 0, 0, 0);
;   od = __builtin_amdgcn_mfma_f32_32x32x16_bf16(pa3, PK(l3, h3), od, 0, 0, 0);
;     ...
; }
; __device__ __forceinline__ void pv_d0(f32x16* o, int vb, bf16x8 pa0, bf16x8 pa1, bf16x8 pa2, bf16x8 pa3) {
;   pv_one<0>(o[0], vb, pa0, pa1, pa2, pa3); pv_one<1>(o[1], vb, pa0, pa1, pa2, pa3); pv_one<2>(o[2], vb, pa0, pa1, pa2, pa3); pv_one<3>(o[3], vb, pa0, pa1, pa2, pa3);
; }
; template <typename TQ> ...
;     ...
;   for (int j = 1; j + 1 < NT; j += 2) {
;     SBAR(); qkt(pB0, pB1, (const bf16*)(K_lds + (j & 3) * (int)SHM_K), qr, r32, hi);
;     finishSM(pA0, pA1, alA, l_reg, pa0, pa1, pa2, pa3); SBAR();
;     DMA_TILE(j + 2, (j + 2) & 3); SBAR();
;     pv_d0(o, vb0 + ((j - 1) & 3) * (int)SHM_V, pa0, pa1, pa2, pa3); partialSM<true>(pB0, pB1, m_reg, mnB, alB);
;     PUBLISH(4);
;     SBAR(); qkt(pA0, pA1, (const bf16*)(K_lds + ((j + 1) & 3) * (int)SHM_K), qr, r32, hi);
;     finishSM(pB0, pB1, alB, l_reg, pa0, pa1, pa2, pa3); SBAR();
;     if (j + 3 < NT) { DMA_TILE(j + 3, (j + 3) & 3); } SBAR();
	v_mfma_f32_32x32x16_bf16 v[96:111], v[230:233], v[112:115], v[96:111]
	s_add_i32 m0, s41, 0x2000
	s_nop 0
	global_load_lds_dwordx4 v158, s[98:99]
	s_mov_b32 m0, s73
	s_nop 0
	global_load_lds_dwordx4 v162, s[100:101]
	s_waitcnt lgkmcnt(8)
	v_mfma_f32_32x32x16_bf16 v[80:95], v[234:237], v[112:115], v[80:95]
	s_add_i32 m0, s73, 0x2000
	s_nop 0
	global_load_lds_dwordx4 v160, s[100:101]
	s_nop 0
	s_waitcnt lgkmcnt(6)
	v_mfma_f32_32x32x16_bf16 v[48:63], v[64:67], v[190:193], v[48:63]
	v_exp_f32_e32 v232, v96
	ds_read_b64_tr_b16 v[190:191], v176 offset:33280
	ds_read_b64_tr_b16 v[192:193], v176 offset:35328
	s_waitcnt lgkmcnt(6)
	v_mfma_f32_32x32x16_bf16 v[48:63], v[68:71], v[194:197], v[48:63]
	v_exp_f32_e32 v233, v97
	ds_read_b64_tr_b16 v[194:195], v176 offset:37376
	ds_read_b64_tr_b16 v[196:197], v176 offset:39424
	s_waitcnt lgkmcnt(6)
	v_mfma_f32_32x32x16_bf16 v[48:63], v[72:75], v[200:203], v[48:63]
	v_exp_f32_e32 v234, v98
	ds_read_b64_tr_b16 v[200:201], v176 offset:41472
	ds_read_b64_tr_b16 v[202:203], v176 offset:43520
	ds_read_b64_tr_b16 v[208:209], v176 offset:45568
	ds_read_b64_tr_b16 v[210:211], v176 offset:47616
	s_waitcnt lgkmcnt(8)
	v_mfma_f32_32x32x16_bf16 v[48:63], v[76:79], v[204:207], v[48:63]
	v_exp_f32_e32 v235, v99
	s_waitcnt lgkmcnt(6)
	v_mfma_f32_32x32x16_bf16 v[32:47], v[64:67], v[190:193], v[32:47]
	v_exp_f32_e32 v236, v100
	ds_read_b64_tr_b16 v[190:191], v176 offset:33792
	ds_read_b64_tr_b16 v[192:193], v176 offset:35840
	s_waitcnt lgkmcnt(6)
	v_mfma_f32_32x32x16_bf16 v[32:47], v[68:71], v[194:197], v[32:47]
	v_exp_f32_e32 v237, v101
	ds_read_b64_tr_b16 v[194:195], v176 offset:37888
	ds_read_b64_tr_b16 v[196:197], v176 offset:39936
	s_waitcnt lgkmcnt(6)
	v_mfma_f32_32x32x16_bf16 v[32:47], v[72:75], v[200:203], v[32:47]
	v_exp_f32_e32 v238, v102
	ds_read_b64_tr_b16 v[200:201], v176 offset:41984
	ds_read_b64_tr_b16 v[202:203], v176 offset:44032
	ds_read_b64_tr_b16 v[204:205], v176 offset:46080
	ds_read_b64_tr_b16 v[206:207], v176 offset:48128
	s_waitcnt lgkmcnt(8)
	v_mfma_f32_32x32x16_bf16 v[32:47], v[76:79], v[208:211], v[32:47]
	v_exp_f32_e32 v239, v103
	v_exp_f32_e32 v240, v104
	s_waitcnt lgkmcnt(6)
	v_mfma_f32_32x32x16_bf16 v[16:31], v[64:67], v[190:193], v[16:31]
	v_exp_f32_e32 v241, v105
	ds_read_b64_tr_b16 v[190:191], v176 offset:34304
	ds_read_b64_tr_b16 v[192:193], v176 offset:36352
	s_waitcnt lgkmcnt(6)
	v_mfma_f32_32x32x16_bf16 v[16:31], v[68:71], v[194:197], v[16:31]
	v_exp_f32_e32 v242, v106
	ds_read_b64_tr_b16 v[194:195], v176 offset:38400
	ds_read_b64_tr_b16 v[196:197], v176 offset:40448
	s_waitcnt lgkmcnt(6)
	v_mfma_f32_32x32x16_bf16 v[16:31], v[72:75], v[200:203], v[16:31]
	v_exp_f32_e32 v243, v107
	ds_read_b64_tr_b16 v[200:201], v176 offset:42496
	ds_read_b64_tr_b16 v[202:203], v176 offset:44544
	ds_read_b64_tr_b16 v[208:209], v176 offset:46592
	ds_read_b64_tr_b16 v[210:211], v176 offset:48640
	s_waitcnt lgkmcnt(8)
	v_mfma_f32_32x32x16_bf16 v[16:31], v[76:79], v[204:207], v[16:31]
	v_exp_f32_e32 v244, v108
	s_waitcnt lgkmcnt(6)
	v_mfma_f32_32x32x16_bf16 v[0:15], v[64:67], v[190:193], v[0:15]
	v_exp_f32_e32 v245, v109
	s_waitcnt lgkmcnt(4)
	v_mfma_f32_32x32x16_bf16 v[0:15], v[68:71], v[194:197], v[0:15]
	v_exp_f32_e32 v246, v110
	s_waitcnt lgkmcnt(2)
	v_mfma_f32_32x32x16_bf16 v[0:15], v[72:75], v[200:203], v[0:15]
	v_exp_f32_e32 v247, v111
	s_waitcnt vmcnt(4)
	s_waitcnt lgkmcnt(0)
	s_barrier
	s_and_b32 s40, s40, 0xc000
	s_add_i32 s40, s56, s40
	ds_read_b128 v[64:67], v178
	ds_read_b128 v[68:71], v178 offset:8192
	ds_read_b128 v[190:193], v179
	ds_read_b128 v[194:197], v179 offset:8192
	v_mfma_f32_32x32x16_bf16 v[0:15], v[76:79], v[208:211], v[0:15]
	s_waitcnt lgkmcnt(3)
	v_mfma_f32_32x32x16_bf16 v[96:111], v[64:67], v[136:139], 0
	v_exp_f32_e32 v80, v80
	v_exp_f32_e32 v81, v81
	v_exp_f32_e32 v82, v82
	v_exp_f32_e32 v83, v83
	v_exp_f32_e32 v87, v87
	v_exp_f32_e32 v248, v93
	v_exp_f32_e32 v249, v94
	s_waitcnt lgkmcnt(2)
	v_mfma_f32_32x32x16_bf16 v[64:79], v[68:71], v[136:139], 0
	s_waitcnt lgkmcnt(1)
	v_mfma_f32_32x32x16_bf16 v[96:111], v[190:193], v[140:143], v[96:111]
	s_waitcnt lgkmcnt(0)
	v_mfma_f32_32x32x16_bf16 v[64:79], v[194:197], v[140:143], v[64:79]
	ds_read_b128 v[190:193], v180
	ds_read_b128 v[194:197], v180 offset:8192
	s_waitcnt lgkmcnt(1)
	v_mfma_f32_32x32x16_bf16 v[96:111], v[190:193], v[132:135], v[96:111]
	ds_read_b128 v[190:193], v181
	ds_read_b128 v[200:203], v181 offset:8192
	ds_read_b128 v[204:207], v182
	ds_read_b128 v[208:211], v182 offset:8192
	ds_read_b128 v[212:215], v183
	ds_read_b128 v[216:219], v183 offset:8192
	s_waitcnt lgkmcnt(6)
	v_mfma_f32_32x32x16_bf16 v[64:79], v[194:197], v[132:135], v[64:79]
	ds_read_b128 v[194:197], v184
	ds_read_b128 v[220:223], v184 offset:8192
	ds_read_b128 v[224:227], v185
	ds_read_b128 v[228:231], v185 offset:8192
	s_waitcnt lgkmcnt(9)
	v_mfma_f32_32x32x16_bf16 v[96:111], v[190:193], v[128:131], v[96:111]
	s_cmp_ge_u32 s72, s37
	s_cselect_b64 s[40:41], -1, 0
	s_and_b64 vcc, exec, s[40:41]
	s_cbranch_vccnz .Lat1367_b

	s_add_i32 s73, s66, s43
	s_add_u32 s98, s38, s26
	s_addc_u32 s99, s39, s27
	s_mov_b32 m0, s73
	s_add_i32 s43, s67, s43
	global_load_lds_dwordx4 v156, s[98:99]
	s_add_u32 s100, s38, s28
	s_addc_u32 s101, s39, s29
	s_add_i32 m0, s73, 0x2000
	s_nop 0
	global_load_lds_dwordx4 v158, s[98:99]
	s_mov_b32 m0, s43
	s_nop 0
	global_load_lds_dwordx4 v162, s[100:101]
	s_add_i32 m0, s43, 0x2000
	s_nop 0
	global_load_lds_dwordx4 v160, s[100:101]
